# hand-scheduled software-pipelined GQA attention phase (PV(t-1)+QK(t+1) MFMAs overlapped with softmax(t) VALU), MLA unchanged
# speedup vs baseline: 1.0183x; 1.0183x over previous
; #define AT_GLOADK(k0) do { kreg = *(const u32x4*)(Kb + (size_t)((k0) + (tid >> 3)) * 64 + (tid & 7) * 8); \
;             if (MLA) preg = *(const u32x2*)(Pb + (size_t)((k0) + (tid >> 3)) * 32 + (tid & 7) * 4); } while (0)
; #define AT_GLOADV(k0) do { vreg = *(const u32x4*)(Vb + (size_t)((k0) + (tid >> 3)) * 64 + (tid & 7) * 8); } while (0)
; #define AT_WRITEK(buf) do { *(LAS u32x4*)(lds + (buf) * KBUF + (tid >> 3) * KSTR + (tid & 7) * 16) = kreg; \
;             if (MLA) *(LAS u32x2*)(lds + (buf) * KBUF + (tid >> 3) * KSTR + 128 + (tid & 7) * 8) = preg; } while (0)
; #define AT_WRITEV(buf) do { *(LAS u32x4*)(lds + 2 * KBUF + (buf) * VBUF + (tid >> 3) * VSTR + (tid & 7) * 16) = vreg; } while (0)
; template <bool MLA>
; DI void attn_phase(const int TID, const int BID, LAS unsigned char* lds, const Params& p, bool need_ctx) {
;     ...
;             const int rnd = item >> 8, w = item & 255, xcd = w & 7, slot = w >> 3, qb = slot & 7;
;             if (MLA) { const int grp = (rnd * 8 + xcd) * 4 + (slot >> 3); b = grp >> 4; head = grp & 15; }
;             else { const int grp = rnd * 8 + xcd; b = grp >> 2; head = (grp & 3) * 4 + (slot >> 3); }
;             row0 = b * 2048 + qb * 256; nk = NKEY;
;         }
;         else { const int it = item - 1024; b = it >> 4; head = it & 15; row0 = TL + b * 256; nk = 256; }
;         const int kvh = MLA ? head : (head >> 2);
;         const bf16_t* Kb = P_WSB(OFF_K) + (size_t)(b * NKV + kvh) * NKEY * 64;
;         const bf16_t* Vb = P_WSB(OFF_VT) + (size_t)(b * NKV + kvh) * NKEY * 64;
;         const bf16_t* Pb = P_WSB(OFF_KPE) + (size_t)b * NKEY * 32;
;         bf16x8 qf[NKS];
;         {
;             const bf16_t* qp = P_WSB(OFF_Q) + (size_t)(row0 + wid * 32 + r) * QS + head * DK + hh * 8;
; #pragma unroll
;             for (int ks = 0; ks < NKS; ++ks) qf[ks] = *(const bf16x8*)(qp + ks * 16);
;         }
;         u32x4 kreg, vreg; u32x2 preg = {0u, 0u};
;     ...
;         f32x16 o0, o1, sa0, sa1, sb0, sb1;
; #pragma unroll
;         for (int j = 0; j < 16; ++j) { o0[j] = 0.f; o1[j] = 0.f; }
;         float mrun = -1e30f, lsum = 0.f;
;         if (wid >= 4) __builtin_amdgcn_s_setprio(1);
;         const int ntile = nk >> 6;
;         AT_GLOADK(0); AT_GLOADV(0); AT_WRITEK(0); AT_WRITEV(0);
;         AT_GLOADK(64); AT_WRITEK(1);
;         __syncthreads();
;         AT_QK(sa0, sa1, 0);
;         __syncthreads();
.LBB0_318:
	s_andn2_b64 vcc, exec, s[4:5]
	s_cbranch_vccnz .LBB0_339
	s_and_b64 vcc, exec, s[2:3]
	s_cbranch_vccnz .LBB0_339
	v_and_b32_e32 v230, 31, v174
	v_bfe_u32 v231, v174, 5, 1
	v_lshrrev_b32_e32 v232, 6, v174
	v_lshrrev_b32_e32 v233, 3, v174
	v_and_b32_e32 v234, 7, v174
	v_mov_b32_e32 v235, s23
	s_movk_i32 s15, 0x90
	v_mad_u32_u24 v229, v230, s15, v235
	v_lshl_add_u32 v229, v231, 4, v229
	v_mad_u32_u24 v218, v233, s15, v235
	v_lshl_add_u32 v218, v234, 4, v218
	s_movk_i32 s15, 0xc0
	v_bfe_u32 v236, v174, 2, 2
	v_lshl_add_u32 v236, v231, 2, v236
	v_mad_u32_u24 v220, v236, s15, v235
	v_bfe_u32 v237, v174, 4, 1
	v_and_b32_e32 v238, 3, v174
	v_lshlrev_b32_e32 v237, 5, v237
	v_lshl_add_u32 v237, v238, 3, v237
	v_add_u32_e32 v220, v220, v237
	v_add_u32_e32 v220, 0x4800, v220
	v_mad_u32_u24 v221, v233, s15, v235
	v_lshl_add_u32 v221, v234, 4, v221
	v_add_u32_e32 v221, 0x4800, v221
	v_lshlrev_b32_e32 v225, 7, v233
	v_lshl_add_u32 v225, v234, 4, v225
	v_lshl_add_u32 v239, v232, 5, v230
	s_movk_i32 s15, 0x800
	v_mul_u32_u24_e32 v227, s15, v239
	v_lshl_add_u32 v227, v231, 4, v227
	v_lshlrev_b32_e32 v228, 11, v239
	v_lshl_add_u32 v228, v231, 4, v228
	v_mov_b32_e32 v167, 0
	v_readfirstlane_b32 s58, v232
	s_mov_b32 s6, s83
	s_lshr_b32 s58, s58, 2
.Lagqa_item:
	s_cmpk_gt_i32 s6, 0x3ff
	s_cbranch_scc0 .Lagqa_mainitem
	s_add_i32 s21, s6, 0xfffffc00
	s_lshr_b32 s15, s21, 4
	s_and_b32 s18, s21, 15
	s_lshl_b32 s20, s15, 8
	s_add_i32 s20, s20, 0x4000
	s_mov_b32 s7, 0
	s_branch .Lagqa_decoded
.Lagqa_mainitem:
	s_lshr_b32 s21, s6, 8
	s_and_b32 s55, s6, 7
	s_lshl_b32 s21, s21, 3
	s_add_i32 s21, s21, s55
	s_bfe_u32 s55, s6, 0x30003
	s_bfe_u32 s56, s6, 0x20006
	s_lshr_b32 s15, s21, 2
	s_and_b32 s57, s21, 3
	s_lshl_b32 s18, s57, 2
	s_add_i32 s18, s18, s56
	s_lshl_b32 s20, s15, 11
	s_lshl_b32 s55, s55, 8
	s_add_i32 s20, s20, s55
	s_mov_b32 s7, 16
.Lagqa_decoded:
	s_lshr_b32 s19, s18, 2
	s_lshl_b32 s21, s15, 2
	s_add_i32 s21, s21, s19
	s_mul_i32 s21, s21, 0x48000
	s_add_u32 s2, s26, s21
	s_addc_u32 s3, s27, 0
	v_readlane_b32 s60, v254, 36
	v_readlane_b32 s61, v254, 37
	s_add_u32 s4, s60, s21
	s_addc_u32 s5, s61, 0
	v_readlane_b32 s60, v254, 27
	v_readlane_b32 s61, v254, 28
	s_mul_i32 s21, s20, 0x800
	s_mul_i32 s55, s18, 0x80
	s_add_i32 s21, s21, s55
	s_add_u32 s12, s60, s21
	s_addc_u32 s13, s61, 0
	v_readlane_b32 s60, v254, 34
	v_readlane_b32 s61, v254, 35
	s_lshl_b32 s21, s20, 11
	s_lshl_b32 s55, s18, 7
	s_add_i32 s21, s21, s55
	s_add_u32 s16, s60, s21
	s_addc_u32 s17, s61, 0
	global_load_dwordx4 v[112:115], v227, s[12:13]
	global_load_dwordx4 v[116:119], v227, s[12:13] offset:32
	global_load_dwordx4 v[120:123], v227, s[12:13] offset:64
	global_load_dwordx4 v[124:127], v227, s[12:13] offset:96
	global_load_dwordx4 v[136:139], v225, s[2:3]
	s_add_u32 s2, s2, 0x2000
	s_addc_u32 s3, s3, 0
	global_load_dwordx4 v[140:143], v225, s[2:3]
	s_add_u32 s2, s2, 0x2000
	s_addc_u32 s3, s3, 0
	global_load_dwordx4 v[144:147], v225, s[4:5]
	s_add_u32 s4, s4, 0x2000
	s_addc_u32 s5, s5, 0
	global_load_dwordx4 v[152:155], v225, s[2:3]
	s_add_u32 s2, s2, 0x2000
	s_addc_u32 s3, s3, 0
	global_load_dwordx4 v[156:159], v225, s[4:5]
	s_add_u32 s4, s4, 0x2000
	s_addc_u32 s5, s5, 0
	s_mov_b32 s52, 0x3000
	s_mov_b32 s53, 0x6000
	s_mov_b32 s54, 0
	v_mov_b64_e32 v[0:1], 0
	v_mov_b64_e32 v[2:3], 0
	v_mov_b64_e32 v[4:5], 0
	v_mov_b64_e32 v[6:7], 0
	v_mov_b64_e32 v[8:9], 0
	v_mov_b64_e32 v[10:11], 0
	v_mov_b64_e32 v[12:13], 0
	v_mov_b64_e32 v[14:15], 0
	v_mov_b64_e32 v[16:17], 0
	v_mov_b64_e32 v[18:19], 0
	v_mov_b64_e32 v[20:21], 0
	v_mov_b64_e32 v[22:23], 0
	v_mov_b64_e32 v[24:25], 0
	v_mov_b64_e32 v[26:27], 0
	v_mov_b64_e32 v[28:29], 0
	v_mov_b64_e32 v[30:31], 0
	v_mov_b32_e32 v162, 0xf149f2ca
	v_mov_b32_e32 v164, 0xf149f2ca
	v_mov_b32_e32 v163, 0x7149f2ca
	v_mov_b32_e32 v165, 0
	s_barrier
	s_waitcnt vmcnt(4)
	ds_write_b128 v218, v[136:139]
	s_waitcnt vmcnt(3)
	ds_write_b128 v218, v[140:143] offset:9216
	s_waitcnt vmcnt(2)
	ds_write_b128 v221, v[144:147]
	s_waitcnt lgkmcnt(0)
	s_barrier
	s_cmp_eq_u32 s58, 0
	s_cbranch_scc1 .Lagqa_prio
	s_setprio 1
.Lagqa_prio:
	ds_read_b128 v[136:139], v229 offset:0
	ds_read_b128 v[140:143], v229 offset:4608
	ds_read_b128 v[144:147], v229 offset:32
	ds_read_b128 v[148:151], v229 offset:4640
	s_waitcnt lgkmcnt(3)
	v_mfma_f32_32x32x16_bf16 v[32:47], v[136:139], v[112:115], 0
	ds_read_b128 v[136:139], v229 offset:64
	s_waitcnt lgkmcnt(3)
	v_mfma_f32_32x32x16_bf16 v[48:63], v[140:143], v[112:115], 0
	ds_read_b128 v[140:143], v229 offset:4672
	s_waitcnt lgkmcnt(3)
	v_mfma_f32_32x32x16_bf16 v[32:47], v[144:147], v[116:119], v[32:47]
	ds_read_b128 v[144:147], v229 offset:96
	s_waitcnt lgkmcnt(3)
	v_mfma_f32_32x32x16_bf16 v[48:63], v[148:151], v[116:119], v[48:63]
	ds_read_b128 v[148:151], v229 offset:4704
	s_waitcnt lgkmcnt(3)
	v_mfma_f32_32x32x16_bf16 v[32:47], v[136:139], v[120:123], v[32:47]
	s_waitcnt lgkmcnt(2)
	v_mfma_f32_32x32x16_bf16 v[48:63], v[140:143], v[120:123], v[48:63]
	s_waitcnt lgkmcnt(1)
	v_mfma_f32_32x32x16_bf16 v[32:47], v[144:147], v[124:127], v[32:47]
	s_waitcnt lgkmcnt(0)
	v_mfma_f32_32x32x16_bf16 v[48:63], v[148:151], v[124:127], v[48:63]
	s_waitcnt lgkmcnt(0)
	s_barrier
	s_mov_b32 s55, s52
	s_mov_b32 s52, s53
	s_mov_b32 s53, s54
	s_mov_b32 s54, s55
	s_mov_b32 s9, 0
	global_load_dwordx4 v[208:211], v225, s[2:3]
	global_load_dwordx4 v[212:215], v225, s[4:5]
	s_add_u32 s2, s2, 0x2000
	s_addc_u32 s3, s3, 0
	s_add_u32 s4, s4, 0x2000
	s_addc_u32 s5, s5, 0
	ds_read_b128 v[136:139], v229 offset:9216
	ds_read_b128 v[140:143], v229 offset:13824
	ds_read_b128 v[144:147], v229 offset:9248
	ds_read_b128 v[148:151], v229 offset:13856
	s_waitcnt lgkmcnt(3)
	v_mfma_f32_32x32x16_bf16 v[64:79], v[136:139], v[112:115], 0
	v_add_u32_e32 v223, s53, v220
	v_add_u32_e32 v224, s54, v221
	v_max3_f32 v168, v32, v33, v34
	v_max3_f32 v170, v48, v49, v50
	v_max3_f32 v168, v168, v35, v36
	v_max3_f32 v170, v170, v51, v52
	v_max3_f32 v168, v168, v37, v38
	v_max3_f32 v170, v170, v53, v54
	v_max3_f32 v168, v168, v39, v40
	v_max3_f32 v170, v170, v55, v56
	ds_read_b128 v[136:139], v229 offset:9280
	s_waitcnt lgkmcnt(3)
	v_mfma_f32_32x32x16_bf16 v[80:95], v[140:143], v[112:115], 0
	v_max3_f32 v168, v168, v41, v42
	v_max3_f32 v170, v170, v57, v58
	v_max3_f32 v168, v168, v43, v44
	v_max3_f32 v170, v170, v59, v60
	v_max3_f32 v168, v168, v45, v46
	v_max3_f32 v170, v170, v61, v62
	v_max_f32_e32 v168, v168, v47
	v_max_f32_e32 v170, v170, v63
	v_max_f32_e32 v168, v168, v170
	v_mov_b32_e32 v170, v168
	s_nop 1
	v_permlane32_swap_b32_e32 v168, v170
	v_max_f32_e32 v168, v168, v170
	v_mul_f32_e32 v168, 0x3e38aa3b, v168
	v_cmp_gt_f32_e32 vcc, v168, v164
	s_cbranch_vccz .Lagqa_nors_1
	v_max_f32_e32 v170, v162, v168
	v_sub_f32_e32 v166, v162, v170
	v_exp_f32_e32 v166, v166
	v_mov_b32_e32 v162, v170
	v_add_f32_e32 v164, 0x41000000, v170
	v_xor_b32_e32 v163, 0x80000000, v170
	v_mul_f32_e32 v165, v165, v166
	s_mov_b32 s9, 1
.Lagqa_nors_1:
	v_fmamk_f32 v32, v32, 0x3e38aa3b, v163
	v_fmamk_f32 v48, v48, 0x3e38aa3b, v163
	ds_read_b128 v[140:143], v229 offset:13888
	s_waitcnt lgkmcnt(3)
	v_mfma_f32_32x32x16_bf16 v[64:79], v[144:147], v[116:119], v[64:79]
	v_exp_f32_e32 v32, v32
	v_exp_f32_e32 v48, v48
	v_fmamk_f32 v33, v33, 0x3e38aa3b, v163
	v_fmamk_f32 v49, v49, 0x3e38aa3b, v163
	v_exp_f32_e32 v33, v33
	v_exp_f32_e32 v49, v49
	v_fmamk_f32 v34, v34, 0x3e38aa3b, v163
	v_fmamk_f32 v50, v50, 0x3e38aa3b, v163
	v_exp_f32_e32 v34, v34
	v_exp_f32_e32 v50, v50
	v_add_f32_e32 v171, v32, v33
	v_add_f32_e32 v172, v48, v49
	v_cvt_pk_bf16_f32 v96, v32, v33
	v_cvt_pk_bf16_f32 v104, v48, v49
	v_fmamk_f32 v35, v35, 0x3e38aa3b, v163
	v_fmamk_f32 v51, v51, 0x3e38aa3b, v163
	v_exp_f32_e32 v35, v35
	ds_read_b128 v[144:147], v229 offset:9312
	s_waitcnt lgkmcnt(3)
	v_mfma_f32_32x32x16_bf16 v[80:95], v[148:151], v[116:119], v[80:95]
	v_exp_f32_e32 v51, v51
	v_fmamk_f32 v36, v36, 0x3e38aa3b, v163
	v_fmamk_f32 v52, v52, 0x3e38aa3b, v163
	v_exp_f32_e32 v36, v36
	v_exp_f32_e32 v52, v52
	v_add_f32_e32 v171, v171, v34
	v_add_f32_e32 v172, v172, v50
	v_add_f32_e32 v171, v171, v35
	v_add_f32_e32 v172, v172, v51
	v_cvt_pk_bf16_f32 v97, v34, v35
	v_cvt_pk_bf16_f32 v105, v50, v51
	v_fmamk_f32 v37, v37, 0x3e38aa3b, v163
	v_fmamk_f32 v53, v53, 0x3e38aa3b, v163
	v_exp_f32_e32 v37, v37
	v_exp_f32_e32 v53, v53
	v_fmamk_f32 v38, v38, 0x3e38aa3b, v163
	v_fmamk_f32 v54, v54, 0x3e38aa3b, v163
	v_exp_f32_e32 v38, v38
	ds_read_b128 v[148:151], v229 offset:13920
	s_waitcnt lgkmcnt(3)
	v_mfma_f32_32x32x16_bf16 v[64:79], v[136:139], v[120:123], v[64:79]
	v_exp_f32_e32 v54, v54
	v_add_f32_e32 v171, v171, v36
	v_add_f32_e32 v172, v172, v52
	v_add_f32_e32 v171, v171, v37
	v_add_f32_e32 v172, v172, v53
	v_cvt_pk_bf16_f32 v98, v36, v37
	v_cvt_pk_bf16_f32 v106, v52, v53
	v_fmamk_f32 v39, v39, 0x3e38aa3b, v163
	v_fmamk_f32 v55, v55, 0x3e38aa3b, v163
	v_exp_f32_e32 v39, v39
	v_exp_f32_e32 v55, v55
	v_fmamk_f32 v40, v40, 0x3e38aa3b, v163
	v_fmamk_f32 v56, v56, 0x3e38aa3b, v163
	v_exp_f32_e32 v40, v40
	v_exp_f32_e32 v56, v56
	v_add_f32_e32 v171, v171, v38
	v_add_f32_e32 v172, v172, v54
	v_add_f32_e32 v171, v171, v39
	s_waitcnt vmcnt(3)
	ds_write_b128 v218, v[152:155]
	s_waitcnt vmcnt(2)
	ds_write_b128 v224, v[156:159]
	s_waitcnt lgkmcnt(4)
	v_mfma_f32_32x32x16_bf16 v[80:95], v[140:143], v[120:123], v[80:95]
	v_add_f32_e32 v172, v172, v55
	v_cvt_pk_bf16_f32 v99, v38, v39
	v_cvt_pk_bf16_f32 v107, v54, v55
	v_fmamk_f32 v41, v41, 0x3e38aa3b, v163
	v_fmamk_f32 v57, v57, 0x3e38aa3b, v163
	v_exp_f32_e32 v41, v41
	v_exp_f32_e32 v57, v57
	v_fmamk_f32 v42, v42, 0x3e38aa3b, v163
	v_fmamk_f32 v58, v58, 0x3e38aa3b, v163
	v_exp_f32_e32 v42, v42
	v_exp_f32_e32 v58, v58
	v_add_f32_e32 v171, v171, v40
	v_add_f32_e32 v172, v172, v56
	v_add_f32_e32 v171, v171, v41
	v_add_f32_e32 v172, v172, v57
	v_cvt_pk_bf16_f32 v100, v40, v41
	v_cvt_pk_bf16_f32 v108, v56, v57
	v_fmamk_f32 v43, v43, 0x3e38aa3b, v163
	v_fmamk_f32 v59, v59, 0x3e38aa3b, v163
	v_exp_f32_e32 v43, v43
	ds_read_b64_tr_b16 v[176:177], v223 offset:0
	ds_read_b64_tr_b16 v[178:179], v223 offset:1536
	ds_read_b64_tr_b16 v[180:181], v223 offset:64
	ds_read_b64_tr_b16 v[182:183], v223 offset:1600
	s_waitcnt lgkmcnt(7)
	v_mfma_f32_32x32x16_bf16 v[64:79], v[144:147], v[124:127], v[64:79]
	v_exp_f32_e32 v59, v59
	v_fmamk_f32 v44, v44, 0x3e38aa3b, v163
	v_fmamk_f32 v60, v60, 0x3e38aa3b, v163
	v_exp_f32_e32 v44, v44
	v_exp_f32_e32 v60, v60
	v_add_f32_e32 v171, v171, v42
	v_add_f32_e32 v172, v172, v58
	v_add_f32_e32 v171, v171, v43
	v_add_f32_e32 v172, v172, v59
	v_cvt_pk_bf16_f32 v101, v42, v43
	v_cvt_pk_bf16_f32 v109, v58, v59
	v_fmamk_f32 v45, v45, 0x3e38aa3b, v163
	v_fmamk_f32 v61, v61, 0x3e38aa3b, v163
	v_exp_f32_e32 v45, v45
	v_exp_f32_e32 v61, v61
	v_fmamk_f32 v46, v46, 0x3e38aa3b, v163
	v_fmamk_f32 v62, v62, 0x3e38aa3b, v163
	v_exp_f32_e32 v46, v46
	s_waitcnt lgkmcnt(6)
	v_mfma_f32_32x32x16_bf16 v[80:95], v[148:151], v[124:127], v[80:95]
	v_exp_f32_e32 v62, v62
	v_add_f32_e32 v171, v171, v44
	v_add_f32_e32 v172, v172, v60
	v_add_f32_e32 v171, v171, v45
	v_add_f32_e32 v172, v172, v61
	v_cvt_pk_bf16_f32 v102, v44, v45
	v_cvt_pk_bf16_f32 v110, v60, v61
	v_fmamk_f32 v47, v47, 0x3e38aa3b, v163
	v_fmamk_f32 v63, v63, 0x3e38aa3b, v163
	v_exp_f32_e32 v47, v47
	v_exp_f32_e32 v63, v63
	v_add_f32_e32 v171, v171, v46
	v_add_f32_e32 v172, v172, v62
	v_add_f32_e32 v171, v171, v47
	v_add_f32_e32 v172, v172, v63
	v_cvt_pk_bf16_f32 v103, v46, v47
	v_cvt_pk_bf16_f32 v111, v62, v63
	v_add_f32_e32 v165, v165, v171
	v_add_f32_e32 v165, v165, v172
	s_waitcnt lgkmcnt(0)
	s_barrier
	s_cmp_eq_u32 s7, 0
	s_cbranch_scc1 .Lagqa_tail
.Lagqa_loop:
	s_mov_b32 s55, s52
	s_mov_b32 s52, s53
	s_mov_b32 s53, s54
	s_mov_b32 s54, s55
	s_mov_b32 s9, 0
	global_load_dwordx4 v[152:155], v225, s[2:3]
	global_load_dwordx4 v[156:159], v225, s[4:5]
	s_add_u32 s2, s2, 0x2000
	s_addc_u32 s3, s3, 0
	s_add_u32 s4, s4, 0x2000
	s_addc_u32 s5, s5, 0
	ds_read_b128 v[136:139], v229 offset:0
	ds_read_b128 v[140:143], v229 offset:4608
	ds_read_b128 v[144:147], v229 offset:32
	ds_read_b128 v[148:151], v229 offset:4640
	v_mfma_f32_32x32x16_bf16 v[0:15], v[176:179], v[96:99], v[0:15]
	v_add_u32_e32 v222, s53, v220
	v_add_u32_e32 v224, s54, v221
	v_max3_f32 v168, v64, v65, v66
	v_max3_f32 v170, v80, v81, v82
	v_max3_f32 v168, v168, v67, v68
	ds_read_b64_tr_b16 v[184:185], v223 offset:6144
	ds_read_b64_tr_b16 v[186:187], v223 offset:7680
	ds_read_b64_tr_b16 v[188:189], v223 offset:6208
	ds_read_b64_tr_b16 v[190:191], v223 offset:7744
	v_mfma_f32_32x32x16_bf16 v[16:31], v[180:183], v[96:99], v[16:31]
	v_max3_f32 v170, v170, v83, v84
	v_max3_f32 v168, v168, v69, v70
	v_max3_f32 v170, v170, v85, v86
	v_max3_f32 v168, v168, v71, v72
	v_max3_f32 v170, v170, v87, v88
	v_max3_f32 v168, v168, v73, v74
	v_max3_f32 v170, v170, v89, v90
	v_max3_f32 v168, v168, v75, v76
	ds_read_b64_tr_b16 v[192:193], v223 offset:3072
	ds_read_b64_tr_b16 v[194:195], v223 offset:4608
	ds_read_b64_tr_b16 v[196:197], v223 offset:3136
	ds_read_b64_tr_b16 v[198:199], v223 offset:4672
	s_waitcnt lgkmcnt(11)
	v_mfma_f32_32x32x16_bf16 v[32:47], v[136:139], v[112:115], 0
	v_max3_f32 v170, v170, v91, v92
	v_max3_f32 v168, v168, v77, v78
	v_max3_f32 v170, v170, v93, v94
	v_max_f32_e32 v168, v168, v79
	v_max_f32_e32 v170, v170, v95
	v_max_f32_e32 v168, v168, v170
	v_mov_b32_e32 v170, v168
	s_nop 1
	v_permlane32_swap_b32_e32 v168, v170
	v_max_f32_e32 v168, v168, v170
	v_mul_f32_e32 v168, 0x3e38aa3b, v168
	v_cmp_gt_f32_e32 vcc, v168, v164
	s_cbranch_vccz .Lagqa_nors_2
	v_max_f32_e32 v170, v162, v168
	v_sub_f32_e32 v166, v162, v170
	v_exp_f32_e32 v166, v166
	v_mov_b32_e32 v162, v170
	v_add_f32_e32 v164, 0x41000000, v170
	v_xor_b32_e32 v163, 0x80000000, v170
	v_mul_f32_e32 v165, v165, v166
	s_mov_b32 s9, 1
.Lagqa_nors_2:
	ds_read_b128 v[136:139], v229 offset:64
	ds_read_b64_tr_b16 v[200:201], v223 offset:9216
	ds_read_b64_tr_b16 v[202:203], v223 offset:10752
	ds_read_b64_tr_b16 v[204:205], v223 offset:9280
	ds_read_b64_tr_b16 v[206:207], v223 offset:10816
	s_waitcnt lgkmcnt(15)
	v_mfma_f32_32x32x16_bf16 v[48:63], v[140:143], v[112:115], 0
	v_fmamk_f32 v64, v64, 0x3e38aa3b, v163
	v_fmamk_f32 v80, v80, 0x3e38aa3b, v163
	v_exp_f32_e32 v64, v64
	v_exp_f32_e32 v80, v80
	v_fmamk_f32 v65, v65, 0x3e38aa3b, v163
	v_fmamk_f32 v81, v81, 0x3e38aa3b, v163
	v_exp_f32_e32 v65, v65
	ds_read_b128 v[140:143], v229 offset:4672
	s_waitcnt lgkmcnt(15)
	v_mfma_f32_32x32x16_bf16 v[32:47], v[144:147], v[116:119], v[32:47]
	v_exp_f32_e32 v81, v81
	v_fmamk_f32 v66, v66, 0x3e38aa3b, v163
	v_fmamk_f32 v82, v82, 0x3e38aa3b, v163
	v_exp_f32_e32 v66, v66
	v_exp_f32_e32 v82, v82
	v_add_f32_e32 v171, v64, v65
	v_add_f32_e32 v172, v80, v81
	v_cvt_pk_bf16_f32 v96, v64, v65
	ds_read_b128 v[144:147], v229 offset:96
	s_waitcnt lgkmcnt(15)
	v_mfma_f32_32x32x16_bf16 v[48:63], v[148:151], v[116:119], v[48:63]
	v_fmamk_f32 v67, v67, 0x3e38aa3b, v163
	v_fmamk_f32 v83, v83, 0x3e38aa3b, v163
	v_exp_f32_e32 v67, v67
	v_exp_f32_e32 v83, v83
	v_fmamk_f32 v68, v68, 0x3e38aa3b, v163
	v_fmamk_f32 v84, v84, 0x3e38aa3b, v163
	v_exp_f32_e32 v68, v68
	v_exp_f32_e32 v84, v84
	ds_read_b128 v[148:151], v229 offset:4704
	s_waitcnt lgkmcnt(7)
	v_mfma_f32_32x32x16_bf16 v[32:47], v[136:139], v[120:123], v[32:47]
	v_add_f32_e32 v171, v171, v66
	v_add_f32_e32 v172, v172, v82
	v_add_f32_e32 v171, v171, v67
	v_add_f32_e32 v172, v172, v83
	v_cvt_pk_bf16_f32 v97, v66, v67
	v_fmamk_f32 v69, v69, 0x3e38aa3b, v163
	v_fmamk_f32 v85, v85, 0x3e38aa3b, v163
	v_exp_f32_e32 v69, v69
	v_exp_f32_e32 v85, v85
	s_waitcnt lgkmcnt(2)
	v_mfma_f32_32x32x16_bf16 v[48:63], v[140:143], v[120:123], v[48:63]
	v_fmamk_f32 v70, v70, 0x3e38aa3b, v163
	v_fmamk_f32 v86, v86, 0x3e38aa3b, v163
	v_exp_f32_e32 v70, v70
	v_exp_f32_e32 v86, v86
	v_add_f32_e32 v171, v171, v68
	v_add_f32_e32 v172, v172, v84
	v_add_f32_e32 v171, v171, v69
	v_add_f32_e32 v172, v172, v85
	v_cvt_pk_bf16_f32 v98, v68, v69
	s_waitcnt lgkmcnt(1)
	v_mfma_f32_32x32x16_bf16 v[32:47], v[144:147], v[124:127], v[32:47]
	v_fmamk_f32 v71, v71, 0x3e38aa3b, v163
	v_fmamk_f32 v87, v87, 0x3e38aa3b, v163
	v_exp_f32_e32 v71, v71
	v_exp_f32_e32 v87, v87
	v_fmamk_f32 v72, v72, 0x3e38aa3b, v163
	v_fmamk_f32 v88, v88, 0x3e38aa3b, v163
	v_exp_f32_e32 v72, v72
	v_exp_f32_e32 v88, v88
	s_waitcnt lgkmcnt(0)
	v_mfma_f32_32x32x16_bf16 v[48:63], v[148:151], v[124:127], v[48:63]
	v_add_f32_e32 v171, v171, v70
	v_add_f32_e32 v172, v172, v86
	v_add_f32_e32 v171, v171, v71
	v_add_f32_e32 v172, v172, v87
	v_cvt_pk_bf16_f32 v99, v70, v71
	v_fmamk_f32 v73, v73, 0x3e38aa3b, v163
	v_fmamk_f32 v89, v89, 0x3e38aa3b, v163
	v_exp_f32_e32 v73, v73
	v_exp_f32_e32 v89, v89
	s_waitcnt vmcnt(3)
	ds_write_b128 v218, v[208:211] offset:9216
	s_waitcnt vmcnt(2)
	ds_write_b128 v224, v[212:215]
	v_mfma_f32_32x32x16_bf16 v[0:15], v[184:187], v[104:107], v[0:15]
	v_fmamk_f32 v74, v74, 0x3e38aa3b, v163
	v_fmamk_f32 v90, v90, 0x3e38aa3b, v163
	v_exp_f32_e32 v74, v74
	v_exp_f32_e32 v90, v90
	v_add_f32_e32 v171, v171, v72
	v_add_f32_e32 v172, v172, v88
	v_add_f32_e32 v171, v171, v73
	v_add_f32_e32 v172, v172, v89
	v_fmamk_f32 v75, v75, 0x3e38aa3b, v163
	v_mfma_f32_32x32x16_bf16 v[16:31], v[188:191], v[104:107], v[16:31]
	v_cvt_pk_bf16_f32 v104, v80, v81
	v_cvt_pk_bf16_f32 v105, v82, v83
	v_cvt_pk_bf16_f32 v106, v84, v85
	v_cvt_pk_bf16_f32 v107, v86, v87
	v_fmamk_f32 v91, v91, 0x3e38aa3b, v163
	v_exp_f32_e32 v75, v75
	v_exp_f32_e32 v91, v91
	v_fmamk_f32 v76, v76, 0x3e38aa3b, v163
	v_fmamk_f32 v92, v92, 0x3e38aa3b, v163
	v_exp_f32_e32 v76, v76
	v_exp_f32_e32 v92, v92
	ds_read_b64_tr_b16 v[176:177], v222 offset:0
	ds_read_b64_tr_b16 v[178:179], v222 offset:1536
	ds_read_b64_tr_b16 v[180:181], v222 offset:64
	ds_read_b64_tr_b16 v[182:183], v222 offset:1600
	v_mfma_f32_32x32x16_bf16 v[0:15], v[192:195], v[100:103], v[0:15]
	v_add_f32_e32 v171, v171, v74
	v_add_f32_e32 v172, v172, v90
	v_add_f32_e32 v171, v171, v75
	v_add_f32_e32 v172, v172, v91
	v_fmamk_f32 v77, v77, 0x3e38aa3b, v163
	v_fmamk_f32 v93, v93, 0x3e38aa3b, v163
	v_exp_f32_e32 v77, v77
	v_exp_f32_e32 v93, v93
	v_fmamk_f32 v78, v78, 0x3e38aa3b, v163
	v_mfma_f32_32x32x16_bf16 v[16:31], v[196:199], v[100:103], v[16:31]
	v_cvt_pk_bf16_f32 v100, v72, v73
	v_cvt_pk_bf16_f32 v101, v74, v75
	v_fmamk_f32 v94, v94, 0x3e38aa3b, v163
	v_exp_f32_e32 v78, v78
	v_exp_f32_e32 v94, v94
	v_add_f32_e32 v171, v171, v76
	v_add_f32_e32 v172, v172, v92
	v_add_f32_e32 v171, v171, v77
	v_add_f32_e32 v172, v172, v93
	v_cvt_pk_bf16_f32 v102, v76, v77
	v_fmamk_f32 v79, v79, 0x3e38aa3b, v163
	v_mfma_f32_32x32x16_bf16 v[0:15], v[200:203], v[108:111], v[0:15]
	v_fmamk_f32 v95, v95, 0x3e38aa3b, v163
	v_exp_f32_e32 v79, v79
	v_exp_f32_e32 v95, v95
	v_add_f32_e32 v171, v171, v78
	v_add_f32_e32 v172, v172, v94
	v_add_f32_e32 v171, v171, v79
	v_add_f32_e32 v172, v172, v95
	v_cvt_pk_bf16_f32 v103, v78, v79
	v_add_f32_e32 v165, v165, v171
	v_mfma_f32_32x32x16_bf16 v[16:31], v[204:207], v[108:111], v[16:31]
	v_cvt_pk_bf16_f32 v108, v88, v89
	v_cvt_pk_bf16_f32 v109, v90, v91
	v_cvt_pk_bf16_f32 v110, v92, v93
	v_cvt_pk_bf16_f32 v111, v94, v95
	v_add_f32_e32 v165, v165, v172
	s_cmp_lg_u32 s9, 0
	s_cbranch_scc0 .Lagqa_noresc_3
	s_nop 15
	v_pk_mul_f32 v[0:1], v[0:1], v[166:167] op_sel_hi:[1,0]
	v_pk_mul_f32 v[2:3], v[2:3], v[166:167] op_sel_hi:[1,0]
	v_pk_mul_f32 v[4:5], v[4:5], v[166:167] op_sel_hi:[1,0]
	v_pk_mul_f32 v[6:7], v[6:7], v[166:167] op_sel_hi:[1,0]
	v_pk_mul_f32 v[8:9], v[8:9], v[166:167] op_sel_hi:[1,0]
	v_pk_mul_f32 v[10:11], v[10:11], v[166:167] op_sel_hi:[1,0]
	v_pk_mul_f32 v[12:13], v[12:13], v[166:167] op_sel_hi:[1,0]
	v_pk_mul_f32 v[14:15], v[14:15], v[166:167] op_sel_hi:[1,0]
	v_pk_mul_f32 v[16:17], v[16:17], v[166:167] op_sel_hi:[1,0]
	v_pk_mul_f32 v[18:19], v[18:19], v[166:167] op_sel_hi:[1,0]
	v_pk_mul_f32 v[20:21], v[20:21], v[166:167] op_sel_hi:[1,0]
	v_pk_mul_f32 v[22:23], v[22:23], v[166:167] op_sel_hi:[1,0]
	v_pk_mul_f32 v[24:25], v[24:25], v[166:167] op_sel_hi:[1,0]
	v_pk_mul_f32 v[26:27], v[26:27], v[166:167] op_sel_hi:[1,0]
	v_pk_mul_f32 v[28:29], v[28:29], v[166:167] op_sel_hi:[1,0]
	v_pk_mul_f32 v[30:31], v[30:31], v[166:167] op_sel_hi:[1,0]
.Lagqa_noresc_3:
	s_waitcnt lgkmcnt(0)
	s_barrier
	s_mov_b32 s55, s52
	s_mov_b32 s52, s53
	s_mov_b32 s53, s54
	s_mov_b32 s54, s55
	s_mov_b32 s9, 0
	global_load_dwordx4 v[208:211], v225, s[2:3]
	global_load_dwordx4 v[212:215], v225, s[4:5]
	s_add_u32 s2, s2, 0x2000
	s_addc_u32 s3, s3, 0
	s_add_u32 s4, s4, 0x2000
	s_addc_u32 s5, s5, 0
	ds_read_b128 v[136:139], v229 offset:9216
	ds_read_b128 v[140:143], v229 offset:13824
	ds_read_b128 v[144:147], v229 offset:9248
	ds_read_b128 v[148:151], v229 offset:13856
	v_mfma_f32_32x32x16_bf16 v[0:15], v[176:179], v[96:99], v[0:15]
	v_add_u32_e32 v223, s53, v220
	v_add_u32_e32 v224, s54, v221
	v_max3_f32 v168, v32, v33, v34
	v_max3_f32 v170, v48, v49, v50
	v_max3_f32 v168, v168, v35, v36
	ds_read_b64_tr_b16 v[184:185], v222 offset:6144
	ds_read_b64_tr_b16 v[186:187], v222 offset:7680
	ds_read_b64_tr_b16 v[188:189], v222 offset:6208
	ds_read_b64_tr_b16 v[190:191], v222 offset:7744
	v_mfma_f32_32x32x16_bf16 v[16:31], v[180:183], v[96:99], v[16:31]
	v_max3_f32 v170, v170, v51, v52
	v_max3_f32 v168, v168, v37, v38
	v_max3_f32 v170, v170, v53, v54
	v_max3_f32 v168, v168, v39, v40
	v_max3_f32 v170, v170, v55, v56
	v_max3_f32 v168, v168, v41, v42
	v_max3_f32 v170, v170, v57, v58
	v_max3_f32 v168, v168, v43, v44
	ds_read_b64_tr_b16 v[192:193], v222 offset:3072
	ds_read_b64_tr_b16 v[194:195], v222 offset:4608
	ds_read_b64_tr_b16 v[196:197], v222 offset:3136
	ds_read_b64_tr_b16 v[198:199], v222 offset:4672
	s_waitcnt lgkmcnt(11)
	v_mfma_f32_32x32x16_bf16 v[64:79], v[136:139], v[112:115], 0
	v_max3_f32 v170, v170, v59, v60
	v_max3_f32 v168, v168, v45, v46
	v_max3_f32 v170, v170, v61, v62
	v_max_f32_e32 v168, v168, v47
	v_max_f32_e32 v170, v170, v63
	v_max_f32_e32 v168, v168, v170
	v_mov_b32_e32 v170, v168
	s_nop 1
	v_permlane32_swap_b32_e32 v168, v170
	v_max_f32_e32 v168, v168, v170
	v_mul_f32_e32 v168, 0x3e38aa3b, v168
	v_cmp_gt_f32_e32 vcc, v168, v164
	s_cbranch_vccz .Lagqa_nors_4
	v_max_f32_e32 v170, v162, v168
	v_sub_f32_e32 v166, v162, v170
	v_exp_f32_e32 v166, v166
	v_mov_b32_e32 v162, v170
	v_add_f32_e32 v164, 0x41000000, v170
	v_xor_b32_e32 v163, 0x80000000, v170
	v_mul_f32_e32 v165, v165, v166
	s_mov_b32 s9, 1
.Lagqa_nors_4:
	ds_read_b128 v[136:139], v229 offset:9280
	ds_read_b64_tr_b16 v[200:201], v222 offset:9216
	ds_read_b64_tr_b16 v[202:203], v222 offset:10752
	ds_read_b64_tr_b16 v[204:205], v222 offset:9280
	ds_read_b64_tr_b16 v[206:207], v222 offset:10816
	s_waitcnt lgkmcnt(15)
	v_mfma_f32_32x32x16_bf16 v[80:95], v[140:143], v[112:115], 0
	v_fmamk_f32 v32, v32, 0x3e38aa3b, v163
	v_fmamk_f32 v48, v48, 0x3e38aa3b, v163
	v_exp_f32_e32 v32, v32
	v_exp_f32_e32 v48, v48
	v_fmamk_f32 v33, v33, 0x3e38aa3b, v163
	v_fmamk_f32 v49, v49, 0x3e38aa3b, v163
	v_exp_f32_e32 v33, v33
	ds_read_b128 v[140:143], v229 offset:13888
	s_waitcnt lgkmcnt(15)
	v_mfma_f32_32x32x16_bf16 v[64:79], v[144:147], v[116:119], v[64:79]
	v_exp_f32_e32 v49, v49
	v_fmamk_f32 v34, v34, 0x3e38aa3b, v163
	v_fmamk_f32 v50, v50, 0x3e38aa3b, v163
	v_exp_f32_e32 v34, v34
	v_exp_f32_e32 v50, v50
	v_add_f32_e32 v171, v32, v33
	v_add_f32_e32 v172, v48, v49
	v_cvt_pk_bf16_f32 v96, v32, v33
	ds_read_b128 v[144:147], v229 offset:9312
	s_waitcnt lgkmcnt(15)
	v_mfma_f32_32x32x16_bf16 v[80:95], v[148:151], v[116:119], v[80:95]
	v_fmamk_f32 v35, v35, 0x3e38aa3b, v163
	v_fmamk_f32 v51, v51, 0x3e38aa3b, v163
	v_exp_f32_e32 v35, v35
	v_exp_f32_e32 v51, v51
	v_fmamk_f32 v36, v36, 0x3e38aa3b, v163
	v_fmamk_f32 v52, v52, 0x3e38aa3b, v163
	v_exp_f32_e32 v36, v36
	v_exp_f32_e32 v52, v52
	ds_read_b128 v[148:151], v229 offset:13920
	s_waitcnt lgkmcnt(7)
	v_mfma_f32_32x32x16_bf16 v[64:79], v[136:139], v[120:123], v[64:79]
	v_add_f32_e32 v171, v171, v34
	v_add_f32_e32 v172, v172, v50
	v_add_f32_e32 v171, v171, v35
	v_add_f32_e32 v172, v172, v51
	v_cvt_pk_bf16_f32 v97, v34, v35
	v_fmamk_f32 v37, v37, 0x3e38aa3b, v163
	v_fmamk_f32 v53, v53, 0x3e38aa3b, v163
	v_exp_f32_e32 v37, v37
	v_exp_f32_e32 v53, v53
	s_waitcnt lgkmcnt(2)
	v_mfma_f32_32x32x16_bf16 v[80:95], v[140:143], v[120:123], v[80:95]
	v_fmamk_f32 v38, v38, 0x3e38aa3b, v163
	v_fmamk_f32 v54, v54, 0x3e38aa3b, v163
	v_exp_f32_e32 v38, v38
	v_exp_f32_e32 v54, v54
	v_add_f32_e32 v171, v171, v36
	v_add_f32_e32 v172, v172, v52
	v_add_f32_e32 v171, v171, v37
	v_add_f32_e32 v172, v172, v53
	v_cvt_pk_bf16_f32 v98, v36, v37
	s_waitcnt lgkmcnt(1)
	v_mfma_f32_32x32x16_bf16 v[64:79], v[144:147], v[124:127], v[64:79]
	v_fmamk_f32 v39, v39, 0x3e38aa3b, v163
	v_fmamk_f32 v55, v55, 0x3e38aa3b, v163
	v_exp_f32_e32 v39, v39
	v_exp_f32_e32 v55, v55
	v_fmamk_f32 v40, v40, 0x3e38aa3b, v163
	v_fmamk_f32 v56, v56, 0x3e38aa3b, v163
	v_exp_f32_e32 v40, v40
	v_exp_f32_e32 v56, v56
	s_waitcnt lgkmcnt(0)
	v_mfma_f32_32x32x16_bf16 v[80:95], v[148:151], v[124:127], v[80:95]
	v_add_f32_e32 v171, v171, v38
	v_add_f32_e32 v172, v172, v54
	v_add_f32_e32 v171, v171, v39
	v_add_f32_e32 v172, v172, v55
	v_cvt_pk_bf16_f32 v99, v38, v39
	v_fmamk_f32 v41, v41, 0x3e38aa3b, v163
	v_fmamk_f32 v57, v57, 0x3e38aa3b, v163
	v_exp_f32_e32 v41, v41
	v_exp_f32_e32 v57, v57
	s_waitcnt vmcnt(3)
	ds_write_b128 v218, v[152:155]
	s_waitcnt vmcnt(2)
	ds_write_b128 v224, v[156:159]
	v_mfma_f32_32x32x16_bf16 v[0:15], v[184:187], v[104:107], v[0:15]
	v_fmamk_f32 v42, v42, 0x3e38aa3b, v163
	v_fmamk_f32 v58, v58, 0x3e38aa3b, v163
	v_exp_f32_e32 v42, v42
	v_exp_f32_e32 v58, v58
	v_add_f32_e32 v171, v171, v40
	v_add_f32_e32 v172, v172, v56
	v_add_f32_e32 v171, v171, v41
	v_add_f32_e32 v172, v172, v57
	v_fmamk_f32 v43, v43, 0x3e38aa3b, v163
	v_mfma_f32_32x32x16_bf16 v[16:31], v[188:191], v[104:107], v[16:31]
	v_cvt_pk_bf16_f32 v104, v48, v49
	v_cvt_pk_bf16_f32 v105, v50, v51
	v_cvt_pk_bf16_f32 v106, v52, v53
	v_cvt_pk_bf16_f32 v107, v54, v55
	v_fmamk_f32 v59, v59, 0x3e38aa3b, v163
	v_exp_f32_e32 v43, v43
	v_exp_f32_e32 v59, v59
	v_fmamk_f32 v44, v44, 0x3e38aa3b, v163
	v_fmamk_f32 v60, v60, 0x3e38aa3b, v163
	v_exp_f32_e32 v44, v44
	v_exp_f32_e32 v60, v60
	ds_read_b64_tr_b16 v[176:177], v223 offset:0
	ds_read_b64_tr_b16 v[178:179], v223 offset:1536
	ds_read_b64_tr_b16 v[180:181], v223 offset:64
	ds_read_b64_tr_b16 v[182:183], v223 offset:1600
	v_mfma_f32_32x32x16_bf16 v[0:15], v[192:195], v[100:103], v[0:15]
	v_add_f32_e32 v171, v171, v42
	v_add_f32_e32 v172, v172, v58
	v_add_f32_e32 v171, v171, v43
	v_add_f32_e32 v172, v172, v59
	v_fmamk_f32 v45, v45, 0x3e38aa3b, v163
	v_fmamk_f32 v61, v61, 0x3e38aa3b, v163
	v_exp_f32_e32 v45, v45
	v_exp_f32_e32 v61, v61
	v_fmamk_f32 v46, v46, 0x3e38aa3b, v163
	v_mfma_f32_32x32x16_bf16 v[16:31], v[196:199], v[100:103], v[16:31]
	v_cvt_pk_bf16_f32 v100, v40, v41
	v_cvt_pk_bf16_f32 v101, v42, v43
	v_fmamk_f32 v62, v62, 0x3e38aa3b, v163
	v_exp_f32_e32 v46, v46
	v_exp_f32_e32 v62, v62
	v_add_f32_e32 v171, v171, v44
	v_add_f32_e32 v172, v172, v60
	v_add_f32_e32 v171, v171, v45
	v_add_f32_e32 v172, v172, v61
	v_cvt_pk_bf16_f32 v102, v44, v45
	v_fmamk_f32 v47, v47, 0x3e38aa3b, v163
	v_mfma_f32_32x32x16_bf16 v[0:15], v[200:203], v[108:111], v[0:15]
	v_fmamk_f32 v63, v63, 0x3e38aa3b, v163
	v_exp_f32_e32 v47, v47
	v_exp_f32_e32 v63, v63
	v_add_f32_e32 v171, v171, v46
	v_add_f32_e32 v172, v172, v62
	v_add_f32_e32 v171, v171, v47
	v_add_f32_e32 v172, v172, v63
	v_cvt_pk_bf16_f32 v103, v46, v47
	v_add_f32_e32 v165, v165, v171
	v_mfma_f32_32x32x16_bf16 v[16:31], v[204:207], v[108:111], v[16:31]
	v_cvt_pk_bf16_f32 v108, v56, v57
	v_cvt_pk_bf16_f32 v109, v58, v59
	v_cvt_pk_bf16_f32 v110, v60, v61
	v_cvt_pk_bf16_f32 v111, v62, v63
	v_add_f32_e32 v165, v165, v172
	s_cmp_lg_u32 s9, 0
	s_cbranch_scc0 .Lagqa_noresc_5
	s_nop 15
	v_pk_mul_f32 v[0:1], v[0:1], v[166:167] op_sel_hi:[1,0]
	v_pk_mul_f32 v[2:3], v[2:3], v[166:167] op_sel_hi:[1,0]
	v_pk_mul_f32 v[4:5], v[4:5], v[166:167] op_sel_hi:[1,0]
	v_pk_mul_f32 v[6:7], v[6:7], v[166:167] op_sel_hi:[1,0]
	v_pk_mul_f32 v[8:9], v[8:9], v[166:167] op_sel_hi:[1,0]
	v_pk_mul_f32 v[10:11], v[10:11], v[166:167] op_sel_hi:[1,0]
	v_pk_mul_f32 v[12:13], v[12:13], v[166:167] op_sel_hi:[1,0]
	v_pk_mul_f32 v[14:15], v[14:15], v[166:167] op_sel_hi:[1,0]
	v_pk_mul_f32 v[16:17], v[16:17], v[166:167] op_sel_hi:[1,0]
	v_pk_mul_f32 v[18:19], v[18:19], v[166:167] op_sel_hi:[1,0]
	v_pk_mul_f32 v[20:21], v[20:21], v[166:167] op_sel_hi:[1,0]
	v_pk_mul_f32 v[22:23], v[22:23], v[166:167] op_sel_hi:[1,0]
	v_pk_mul_f32 v[24:25], v[24:25], v[166:167] op_sel_hi:[1,0]
	v_pk_mul_f32 v[26:27], v[26:27], v[166:167] op_sel_hi:[1,0]
	v_pk_mul_f32 v[28:29], v[28:29], v[166:167] op_sel_hi:[1,0]
	v_pk_mul_f32 v[30:31], v[30:31], v[166:167] op_sel_hi:[1,0]
; #define AT_STEP(SC0, SC1, SN0, SN1, t, DOK, DOV) do { \
;             if (DOK) AT_GLOADK(((t) + 2) * 64); \
;             if (DOV) { AT_GLOADV(((t) + 1) * 64); AT_QK(SN0, SN1, ((t) + 1) & 1); } \
;             AT_SMPV(SC0, SC1, (t) & 1); \
;             if (DOK) AT_WRITEK((t) & 1); \
;             if (DOV) AT_WRITEV(((t) + 1) & 1); \
;             __syncthreads(); } while (0)
; template <bool MLA>
; DI void attn_phase(const int TID, const int BID, LAS unsigned char* lds, const Params& p, bool need_ctx) {
;     ...
;         for (; t < ntile - 2; t += 2) {
;             AT_STEP(sa0, sa1, sb0, sb1, t, true, true);
;             AT_STEP(sb0, sb1, sa0, sa1, t + 1, true, true);
;         }
;         AT_STEP(sa0, sa1, sb0, sb1, t, false, true);
;         AT_STEP(sb0, sb1, sa0, sa1, t + 1, false, false);
.Lagqa_noresc_5:
	s_waitcnt lgkmcnt(0)
	s_barrier
	s_add_i32 s7, s7, -1
	s_cmp_lg_u32 s7, 0
	s_cbranch_scc1 .Lagqa_loop
.Lagqa_tail:
	s_mov_b32 s55, s52
	s_mov_b32 s52, s53
	s_mov_b32 s53, s54
	s_mov_b32 s54, s55
	s_mov_b32 s9, 0
	global_load_dwordx4 v[156:159], v225, s[4:5]
	s_add_u32 s4, s4, 0x2000
	s_addc_u32 s5, s5, 0
	ds_read_b128 v[136:139], v229 offset:0
	ds_read_b128 v[140:143], v229 offset:4608
	ds_read_b128 v[144:147], v229 offset:32
	ds_read_b128 v[148:151], v229 offset:4640
	v_mfma_f32_32x32x16_bf16 v[0:15], v[176:179], v[96:99], v[0:15]
	v_add_u32_e32 v222, s53, v220
	v_add_u32_e32 v224, s54, v221
	v_max3_f32 v168, v64, v65, v66
	v_max3_f32 v170, v80, v81, v82
	v_max3_f32 v168, v168, v67, v68
	ds_read_b64_tr_b16 v[184:185], v223 offset:6144
	ds_read_b64_tr_b16 v[186:187], v223 offset:7680
	ds_read_b64_tr_b16 v[188:189], v223 offset:6208
	ds_read_b64_tr_b16 v[190:191], v223 offset:7744
	v_mfma_f32_32x32x16_bf16 v[16:31], v[180:183], v[96:99], v[16:31]
	v_max3_f32 v170, v170, v83, v84
	v_max3_f32 v168, v168, v69, v70
	v_max3_f32 v170, v170, v85, v86
	v_max3_f32 v168, v168, v71, v72
	v_max3_f32 v170, v170, v87, v88
	v_max3_f32 v168, v168, v73, v74
	v_max3_f32 v170, v170, v89, v90
	v_max3_f32 v168, v168, v75, v76
	ds_read_b64_tr_b16 v[192:193], v223 offset:3072
	ds_read_b64_tr_b16 v[194:195], v223 offset:4608
	ds_read_b64_tr_b16 v[196:197], v223 offset:3136
	ds_read_b64_tr_b16 v[198:199], v223 offset:4672
	s_waitcnt lgkmcnt(11)
	v_mfma_f32_32x32x16_bf16 v[32:47], v[136:139], v[112:115], 0
	v_max3_f32 v170, v170, v91, v92
	v_max3_f32 v168, v168, v77, v78
	v_max3_f32 v170, v170, v93, v94
	v_max_f32_e32 v168, v168, v79
	v_max_f32_e32 v170, v170, v95
	v_max_f32_e32 v168, v168, v170
	v_mov_b32_e32 v170, v168
	s_nop 1
	v_permlane32_swap_b32_e32 v168, v170
	v_max_f32_e32 v168, v168, v170
	v_mul_f32_e32 v168, 0x3e38aa3b, v168
	v_cmp_gt_f32_e32 vcc, v168, v164
	s_cbranch_vccz .Lagqa_nors_6
	v_max_f32_e32 v170, v162, v168
	v_sub_f32_e32 v166, v162, v170
	v_exp_f32_e32 v166, v166
	v_mov_b32_e32 v162, v170
	v_add_f32_e32 v164, 0x41000000, v170
	v_xor_b32_e32 v163, 0x80000000, v170
	v_mul_f32_e32 v165, v165, v166
	s_mov_b32 s9, 1
.Lagqa_nors_6:
	ds_read_b128 v[136:139], v229 offset:64
	ds_read_b64_tr_b16 v[200:201], v223 offset:9216
	ds_read_b64_tr_b16 v[202:203], v223 offset:10752
	ds_read_b64_tr_b16 v[204:205], v223 offset:9280
	ds_read_b64_tr_b16 v[206:207], v223 offset:10816
	s_waitcnt lgkmcnt(15)
	v_mfma_f32_32x32x16_bf16 v[48:63], v[140:143], v[112:115], 0
	v_fmamk_f32 v64, v64, 0x3e38aa3b, v163
	v_fmamk_f32 v80, v80, 0x3e38aa3b, v163
	v_exp_f32_e32 v64, v64
	v_exp_f32_e32 v80, v80
	v_fmamk_f32 v65, v65, 0x3e38aa3b, v163
	v_fmamk_f32 v81, v81, 0x3e38aa3b, v163
	v_exp_f32_e32 v65, v65
	ds_read_b128 v[140:143], v229 offset:4672
	s_waitcnt lgkmcnt(15)
	v_mfma_f32_32x32x16_bf16 v[32:47], v[144:147], v[116:119], v[32:47]
	v_exp_f32_e32 v81, v81
	v_fmamk_f32 v66, v66, 0x3e38aa3b, v163
	v_fmamk_f32 v82, v82, 0x3e38aa3b, v163
	v_exp_f32_e32 v66, v66
	v_exp_f32_e32 v82, v82
	v_add_f32_e32 v171, v64, v65
	v_add_f32_e32 v172, v80, v81
	v_cvt_pk_bf16_f32 v96, v64, v65
	ds_read_b128 v[144:147], v229 offset:96
	s_waitcnt lgkmcnt(15)
	v_mfma_f32_32x32x16_bf16 v[48:63], v[148:151], v[116:119], v[48:63]
	v_fmamk_f32 v67, v67, 0x3e38aa3b, v163
	v_fmamk_f32 v83, v83, 0x3e38aa3b, v163
	v_exp_f32_e32 v67, v67
	v_exp_f32_e32 v83, v83
	v_fmamk_f32 v68, v68, 0x3e38aa3b, v163
	v_fmamk_f32 v84, v84, 0x3e38aa3b, v163
	v_exp_f32_e32 v68, v68
	v_exp_f32_e32 v84, v84
	ds_read_b128 v[148:151], v229 offset:4704
	s_waitcnt lgkmcnt(7)
	v_mfma_f32_32x32x16_bf16 v[32:47], v[136:139], v[120:123], v[32:47]
	v_add_f32_e32 v171, v171, v66
	v_add_f32_e32 v172, v172, v82
	v_add_f32_e32 v171, v171, v67
	v_add_f32_e32 v172, v172, v83
	v_cvt_pk_bf16_f32 v97, v66, v67
	v_fmamk_f32 v69, v69, 0x3e38aa3b, v163
	v_fmamk_f32 v85, v85, 0x3e38aa3b, v163
	v_exp_f32_e32 v69, v69
	v_exp_f32_e32 v85, v85
	s_waitcnt lgkmcnt(2)
	v_mfma_f32_32x32x16_bf16 v[48:63], v[140:143], v[120:123], v[48:63]
	v_fmamk_f32 v70, v70, 0x3e38aa3b, v163
	v_fmamk_f32 v86, v86, 0x3e38aa3b, v163
	v_exp_f32_e32 v70, v70
	v_exp_f32_e32 v86, v86
	v_add_f32_e32 v171, v171, v68
	v_add_f32_e32 v172, v172, v84
	v_add_f32_e32 v171, v171, v69
	v_add_f32_e32 v172, v172, v85
	v_cvt_pk_bf16_f32 v98, v68, v69
	s_waitcnt lgkmcnt(1)
	v_mfma_f32_32x32x16_bf16 v[32:47], v[144:147], v[124:127], v[32:47]
	v_fmamk_f32 v71, v71, 0x3e38aa3b, v163
	v_fmamk_f32 v87, v87, 0x3e38aa3b, v163
	v_exp_f32_e32 v71, v71
	v_exp_f32_e32 v87, v87
	v_fmamk_f32 v72, v72, 0x3e38aa3b, v163
	v_fmamk_f32 v88, v88, 0x3e38aa3b, v163
	v_exp_f32_e32 v72, v72
	v_exp_f32_e32 v88, v88
	s_waitcnt lgkmcnt(0)
	v_mfma_f32_32x32x16_bf16 v[48:63], v[148:151], v[124:127], v[48:63]
	v_add_f32_e32 v171, v171, v70
	v_add_f32_e32 v172, v172, v86
	v_add_f32_e32 v171, v171, v71
	v_add_f32_e32 v172, v172, v87
	v_cvt_pk_bf16_f32 v99, v70, v71
	v_fmamk_f32 v73, v73, 0x3e38aa3b, v163
	v_fmamk_f32 v89, v89, 0x3e38aa3b, v163
	v_exp_f32_e32 v73, v73
	v_exp_f32_e32 v89, v89
	s_waitcnt vmcnt(2)
	ds_write_b128 v218, v[208:211] offset:9216
	s_waitcnt vmcnt(1)
	ds_write_b128 v224, v[212:215]
	v_mfma_f32_32x32x16_bf16 v[0:15], v[184:187], v[104:107], v[0:15]
	v_fmamk_f32 v74, v74, 0x3e38aa3b, v163
	v_fmamk_f32 v90, v90, 0x3e38aa3b, v163
	v_exp_f32_e32 v74, v74
	v_exp_f32_e32 v90, v90
	v_add_f32_e32 v171, v171, v72
	v_add_f32_e32 v172, v172, v88
	v_add_f32_e32 v171, v171, v73
	v_add_f32_e32 v172, v172, v89
	v_fmamk_f32 v75, v75, 0x3e38aa3b, v163
	v_mfma_f32_32x32x16_bf16 v[16:31], v[188:191], v[104:107], v[16:31]
	v_cvt_pk_bf16_f32 v104, v80, v81
	v_cvt_pk_bf16_f32 v105, v82, v83
	v_cvt_pk_bf16_f32 v106, v84, v85
	v_cvt_pk_bf16_f32 v107, v86, v87
	v_fmamk_f32 v91, v91, 0x3e38aa3b, v163
	v_exp_f32_e32 v75, v75
	v_exp_f32_e32 v91, v91
	v_fmamk_f32 v76, v76, 0x3e38aa3b, v163
	v_fmamk_f32 v92, v92, 0x3e38aa3b, v163
	v_exp_f32_e32 v76, v76
	v_exp_f32_e32 v92, v92
	ds_read_b64_tr_b16 v[176:177], v222 offset:0
	ds_read_b64_tr_b16 v[178:179], v222 offset:1536
	ds_read_b64_tr_b16 v[180:181], v222 offset:64
	ds_read_b64_tr_b16 v[182:183], v222 offset:1600
	v_mfma_f32_32x32x16_bf16 v[0:15], v[192:195], v[100:103], v[0:15]
	v_add_f32_e32 v171, v171, v74
	v_add_f32_e32 v172, v172, v90
	v_add_f32_e32 v171, v171, v75
	v_add_f32_e32 v172, v172, v91
	v_fmamk_f32 v77, v77, 0x3e38aa3b, v163
	v_fmamk_f32 v93, v93, 0x3e38aa3b, v163
	v_exp_f32_e32 v77, v77
	v_exp_f32_e32 v93, v93
	v_fmamk_f32 v78, v78, 0x3e38aa3b, v163
	v_mfma_f32_32x32x16_bf16 v[16:31], v[196:199], v[100:103], v[16:31]
	v_cvt_pk_bf16_f32 v100, v72, v73
	v_cvt_pk_bf16_f32 v101, v74, v75
	v_fmamk_f32 v94, v94, 0x3e38aa3b, v163
	v_exp_f32_e32 v78, v78
	v_exp_f32_e32 v94, v94
	v_add_f32_e32 v171, v171, v76
	v_add_f32_e32 v172, v172, v92
	v_add_f32_e32 v171, v171, v77
	v_add_f32_e32 v172, v172, v93
	v_cvt_pk_bf16_f32 v102, v76, v77
	v_fmamk_f32 v79, v79, 0x3e38aa3b, v163
	v_mfma_f32_32x32x16_bf16 v[0:15], v[200:203], v[108:111], v[0:15]
	v_fmamk_f32 v95, v95, 0x3e38aa3b, v163
	v_exp_f32_e32 v79, v79
	v_exp_f32_e32 v95, v95
	v_add_f32_e32 v171, v171, v78
	v_add_f32_e32 v172, v172, v94
	v_add_f32_e32 v171, v171, v79
	v_add_f32_e32 v172, v172, v95
	v_cvt_pk_bf16_f32 v103, v78, v79
	v_add_f32_e32 v165, v165, v171
	v_mfma_f32_32x32x16_bf16 v[16:31], v[204:207], v[108:111], v[16:31]
	v_cvt_pk_bf16_f32 v108, v88, v89
	v_cvt_pk_bf16_f32 v109, v90, v91
	v_cvt_pk_bf16_f32 v110, v92, v93
	v_cvt_pk_bf16_f32 v111, v94, v95
	v_add_f32_e32 v165, v165, v172
	s_cmp_lg_u32 s9, 0
	s_cbranch_scc0 .Lagqa_noresc_7
	s_nop 15
	v_pk_mul_f32 v[0:1], v[0:1], v[166:167] op_sel_hi:[1,0]
	v_pk_mul_f32 v[2:3], v[2:3], v[166:167] op_sel_hi:[1,0]
	v_pk_mul_f32 v[4:5], v[4:5], v[166:167] op_sel_hi:[1,0]
	v_pk_mul_f32 v[6:7], v[6:7], v[166:167] op_sel_hi:[1,0]
	v_pk_mul_f32 v[8:9], v[8:9], v[166:167] op_sel_hi:[1,0]
	v_pk_mul_f32 v[10:11], v[10:11], v[166:167] op_sel_hi:[1,0]
	v_pk_mul_f32 v[12:13], v[12:13], v[166:167] op_sel_hi:[1,0]
	v_pk_mul_f32 v[14:15], v[14:15], v[166:167] op_sel_hi:[1,0]
	v_pk_mul_f32 v[16:17], v[16:17], v[166:167] op_sel_hi:[1,0]
	v_pk_mul_f32 v[18:19], v[18:19], v[166:167] op_sel_hi:[1,0]
	v_pk_mul_f32 v[20:21], v[20:21], v[166:167] op_sel_hi:[1,0]
	v_pk_mul_f32 v[22:23], v[22:23], v[166:167] op_sel_hi:[1,0]
	v_pk_mul_f32 v[24:25], v[24:25], v[166:167] op_sel_hi:[1,0]
	v_pk_mul_f32 v[26:27], v[26:27], v[166:167] op_sel_hi:[1,0]
	v_pk_mul_f32 v[28:29], v[28:29], v[166:167] op_sel_hi:[1,0]
	v_pk_mul_f32 v[30:31], v[30:31], v[166:167] op_sel_hi:[1,0]
.Lagqa_noresc_7:
	s_waitcnt lgkmcnt(0)
	s_barrier
	s_mov_b32 s55, s52
	s_mov_b32 s52, s53
	s_mov_b32 s53, s54
	s_mov_b32 s54, s55
	s_mov_b32 s9, 0
	ds_read_b128 v[136:139], v229 offset:9216
	ds_read_b128 v[140:143], v229 offset:13824
	ds_read_b128 v[144:147], v229 offset:9248
	ds_read_b128 v[148:151], v229 offset:13856
	v_mfma_f32_32x32x16_bf16 v[0:15], v[176:179], v[96:99], v[0:15]
	v_add_u32_e32 v223, s53, v220
	v_add_u32_e32 v224, s54, v221
	v_max3_f32 v168, v32, v33, v34
	v_max3_f32 v170, v48, v49, v50
	v_max3_f32 v168, v168, v35, v36
	ds_read_b64_tr_b16 v[184:185], v222 offset:6144
	ds_read_b64_tr_b16 v[186:187], v222 offset:7680
	ds_read_b64_tr_b16 v[188:189], v222 offset:6208
	ds_read_b64_tr_b16 v[190:191], v222 offset:7744
	v_mfma_f32_32x32x16_bf16 v[16:31], v[180:183], v[96:99], v[16:31]
	v_max3_f32 v170, v170, v51, v52
	v_max3_f32 v168, v168, v37, v38
	v_max3_f32 v170, v170, v53, v54
	v_max3_f32 v168, v168, v39, v40
	v_max3_f32 v170, v170, v55, v56
	v_max3_f32 v168, v168, v41, v42
	v_max3_f32 v170, v170, v57, v58
	v_max3_f32 v168, v168, v43, v44
	ds_read_b64_tr_b16 v[192:193], v222 offset:3072
	ds_read_b64_tr_b16 v[194:195], v222 offset:4608
	ds_read_b64_tr_b16 v[196:197], v222 offset:3136
	ds_read_b64_tr_b16 v[198:199], v222 offset:4672
	s_waitcnt lgkmcnt(11)
	v_mfma_f32_32x32x16_bf16 v[64:79], v[136:139], v[112:115], 0
	v_max3_f32 v170, v170, v59, v60
	v_max3_f32 v168, v168, v45, v46
	v_max3_f32 v170, v170, v61, v62
	v_max_f32_e32 v168, v168, v47
	v_max_f32_e32 v170, v170, v63
	v_max_f32_e32 v168, v168, v170
	v_mov_b32_e32 v170, v168
	s_nop 1
	v_permlane32_swap_b32_e32 v168, v170
	v_max_f32_e32 v168, v168, v170
	v_mul_f32_e32 v168, 0x3e38aa3b, v168
	v_cmp_gt_f32_e32 vcc, v168, v164
	s_cbranch_vccz .Lagqa_nors_8
	v_max_f32_e32 v170, v162, v168
	v_sub_f32_e32 v166, v162, v170
	v_exp_f32_e32 v166, v166
	v_mov_b32_e32 v162, v170
	v_add_f32_e32 v164, 0x41000000, v170
	v_xor_b32_e32 v163, 0x80000000, v170
	v_mul_f32_e32 v165, v165, v166
	s_mov_b32 s9, 1
.Lagqa_nors_8:
	ds_read_b128 v[136:139], v229 offset:9280
	ds_read_b64_tr_b16 v[200:201], v222 offset:9216
	ds_read_b64_tr_b16 v[202:203], v222 offset:10752
	ds_read_b64_tr_b16 v[204:205], v222 offset:9280
	ds_read_b64_tr_b16 v[206:207], v222 offset:10816
	s_waitcnt lgkmcnt(15)
	v_mfma_f32_32x32x16_bf16 v[80:95], v[140:143], v[112:115], 0
	v_fmamk_f32 v32, v32, 0x3e38aa3b, v163
	v_fmamk_f32 v48, v48, 0x3e38aa3b, v163
	v_exp_f32_e32 v32, v32
	v_exp_f32_e32 v48, v48
	v_fmamk_f32 v33, v33, 0x3e38aa3b, v163
	v_fmamk_f32 v49, v49, 0x3e38aa3b, v163
	v_exp_f32_e32 v33, v33
	ds_read_b128 v[140:143], v229 offset:13888
	s_waitcnt lgkmcnt(15)
	v_mfma_f32_32x32x16_bf16 v[64:79], v[144:147], v[116:119], v[64:79]
	v_exp_f32_e32 v49, v49
	v_fmamk_f32 v34, v34, 0x3e38aa3b, v163
	v_fmamk_f32 v50, v50, 0x3e38aa3b, v163
	v_exp_f32_e32 v34, v34
	v_exp_f32_e32 v50, v50
	v_add_f32_e32 v171, v32, v33
	v_add_f32_e32 v172, v48, v49
	v_cvt_pk_bf16_f32 v96, v32, v33
	ds_read_b128 v[144:147], v229 offset:9312
	s_waitcnt lgkmcnt(15)
	v_mfma_f32_32x32x16_bf16 v[80:95], v[148:151], v[116:119], v[80:95]
	v_fmamk_f32 v35, v35, 0x3e38aa3b, v163
	v_fmamk_f32 v51, v51, 0x3e38aa3b, v163
	v_exp_f32_e32 v35, v35
	v_exp_f32_e32 v51, v51
	v_fmamk_f32 v36, v36, 0x3e38aa3b, v163
	v_fmamk_f32 v52, v52, 0x3e38aa3b, v163
	v_exp_f32_e32 v36, v36
	v_exp_f32_e32 v52, v52
	ds_read_b128 v[148:151], v229 offset:13920
	s_waitcnt lgkmcnt(7)
	v_mfma_f32_32x32x16_bf16 v[64:79], v[136:139], v[120:123], v[64:79]
	v_add_f32_e32 v171, v171, v34
	v_add_f32_e32 v172, v172, v50
	v_add_f32_e32 v171, v171, v35
	v_add_f32_e32 v172, v172, v51
	v_cvt_pk_bf16_f32 v97, v34, v35
	v_fmamk_f32 v37, v37, 0x3e38aa3b, v163
	v_fmamk_f32 v53, v53, 0x3e38aa3b, v163
	v_exp_f32_e32 v37, v37
	v_exp_f32_e32 v53, v53
	s_waitcnt lgkmcnt(2)
	v_mfma_f32_32x32x16_bf16 v[80:95], v[140:143], v[120:123], v[80:95]
	v_fmamk_f32 v38, v38, 0x3e38aa3b, v163
	v_fmamk_f32 v54, v54, 0x3e38aa3b, v163
	v_exp_f32_e32 v38, v38
	v_exp_f32_e32 v54, v54
	v_add_f32_e32 v171, v171, v36
	v_add_f32_e32 v172, v172, v52
	v_add_f32_e32 v171, v171, v37
	v_add_f32_e32 v172, v172, v53
	v_cvt_pk_bf16_f32 v98, v36, v37
	s_waitcnt lgkmcnt(1)
	v_mfma_f32_32x32x16_bf16 v[64:79], v[144:147], v[124:127], v[64:79]
	v_fmamk_f32 v39, v39, 0x3e38aa3b, v163
	v_fmamk_f32 v55, v55, 0x3e38aa3b, v163
	v_exp_f32_e32 v39, v39
	v_exp_f32_e32 v55, v55
	v_fmamk_f32 v40, v40, 0x3e38aa3b, v163
	v_fmamk_f32 v56, v56, 0x3e38aa3b, v163
	v_exp_f32_e32 v40, v40
	v_exp_f32_e32 v56, v56
	s_waitcnt lgkmcnt(0)
	v_mfma_f32_32x32x16_bf16 v[80:95], v[148:151], v[124:127], v[80:95]
	v_add_f32_e32 v171, v171, v38
	v_add_f32_e32 v172, v172, v54
	v_add_f32_e32 v171, v171, v39
	v_add_f32_e32 v172, v172, v55
	v_cvt_pk_bf16_f32 v99, v38, v39
	v_fmamk_f32 v41, v41, 0x3e38aa3b, v163
	v_fmamk_f32 v57, v57, 0x3e38aa3b, v163
	v_exp_f32_e32 v41, v41
	v_exp_f32_e32 v57, v57
	s_waitcnt vmcnt(0)
	ds_write_b128 v224, v[156:159]
	v_mfma_f32_32x32x16_bf16 v[0:15], v[184:187], v[104:107], v[0:15]
	v_fmamk_f32 v42, v42, 0x3e38aa3b, v163
	v_fmamk_f32 v58, v58, 0x3e38aa3b, v163
	v_exp_f32_e32 v42, v42
	v_exp_f32_e32 v58, v58
	v_add_f32_e32 v171, v171, v40
	v_add_f32_e32 v172, v172, v56
	v_add_f32_e32 v171, v171, v41
	v_add_f32_e32 v172, v172, v57
	v_fmamk_f32 v43, v43, 0x3e38aa3b, v163
	v_mfma_f32_32x32x16_bf16 v[16:31], v[188:191], v[104:107], v[16:31]
	v_cvt_pk_bf16_f32 v104, v48, v49
	v_cvt_pk_bf16_f32 v105, v50, v51
	v_cvt_pk_bf16_f32 v106, v52, v53
	v_cvt_pk_bf16_f32 v107, v54, v55
	v_fmamk_f32 v59, v59, 0x3e38aa3b, v163
	v_exp_f32_e32 v43, v43
	v_exp_f32_e32 v59, v59
	v_fmamk_f32 v44, v44, 0x3e38aa3b, v163
	v_fmamk_f32 v60, v60, 0x3e38aa3b, v163
	v_exp_f32_e32 v44, v44
	v_exp_f32_e32 v60, v60
	ds_read_b64_tr_b16 v[176:177], v223 offset:0
	ds_read_b64_tr_b16 v[178:179], v223 offset:1536
	ds_read_b64_tr_b16 v[180:181], v223 offset:64
	ds_read_b64_tr_b16 v[182:183], v223 offset:1600
	v_mfma_f32_32x32x16_bf16 v[0:15], v[192:195], v[100:103], v[0:15]
	v_add_f32_e32 v171, v171, v42
	v_add_f32_e32 v172, v172, v58
	v_add_f32_e32 v171, v171, v43
	v_add_f32_e32 v172, v172, v59
	v_fmamk_f32 v45, v45, 0x3e38aa3b, v163
	v_fmamk_f32 v61, v61, 0x3e38aa3b, v163
	v_exp_f32_e32 v45, v45
	v_exp_f32_e32 v61, v61
	v_fmamk_f32 v46, v46, 0x3e38aa3b, v163
	v_mfma_f32_32x32x16_bf16 v[16:31], v[196:199], v[100:103], v[16:31]
	v_cvt_pk_bf16_f32 v100, v40, v41
	v_cvt_pk_bf16_f32 v101, v42, v43
	v_fmamk_f32 v62, v62, 0x3e38aa3b, v163
	v_exp_f32_e32 v46, v46
	v_exp_f32_e32 v62, v62
	v_add_f32_e32 v171, v171, v44
	v_add_f32_e32 v172, v172, v60
	v_add_f32_e32 v171, v171, v45
	v_add_f32_e32 v172, v172, v61
	v_cvt_pk_bf16_f32 v102, v44, v45
	v_fmamk_f32 v47, v47, 0x3e38aa3b, v163
	v_mfma_f32_32x32x16_bf16 v[0:15], v[200:203], v[108:111], v[0:15]
	v_fmamk_f32 v63, v63, 0x3e38aa3b, v163
	v_exp_f32_e32 v47, v47
	v_exp_f32_e32 v63, v63
	v_add_f32_e32 v171, v171, v46
	v_add_f32_e32 v172, v172, v62
	v_add_f32_e32 v171, v171, v47
	v_add_f32_e32 v172, v172, v63
	v_cvt_pk_bf16_f32 v103, v46, v47
	v_add_f32_e32 v165, v165, v171
	v_mfma_f32_32x32x16_bf16 v[16:31], v[204:207], v[108:111], v[16:31]
	v_cvt_pk_bf16_f32 v108, v56, v57
	v_cvt_pk_bf16_f32 v109, v58, v59
	v_cvt_pk_bf16_f32 v110, v60, v61
	v_cvt_pk_bf16_f32 v111, v62, v63
	v_add_f32_e32 v165, v165, v172
	s_cmp_lg_u32 s9, 0
	s_cbranch_scc0 .Lagqa_noresc_9
	s_nop 15
	v_pk_mul_f32 v[0:1], v[0:1], v[166:167] op_sel_hi:[1,0]
	v_pk_mul_f32 v[2:3], v[2:3], v[166:167] op_sel_hi:[1,0]
	v_pk_mul_f32 v[4:5], v[4:5], v[166:167] op_sel_hi:[1,0]
	v_pk_mul_f32 v[6:7], v[6:7], v[166:167] op_sel_hi:[1,0]
	v_pk_mul_f32 v[8:9], v[8:9], v[166:167] op_sel_hi:[1,0]
	v_pk_mul_f32 v[10:11], v[10:11], v[166:167] op_sel_hi:[1,0]
	v_pk_mul_f32 v[12:13], v[12:13], v[166:167] op_sel_hi:[1,0]
	v_pk_mul_f32 v[14:15], v[14:15], v[166:167] op_sel_hi:[1,0]
	v_pk_mul_f32 v[16:17], v[16:17], v[166:167] op_sel_hi:[1,0]
	v_pk_mul_f32 v[18:19], v[18:19], v[166:167] op_sel_hi:[1,0]
	v_pk_mul_f32 v[20:21], v[20:21], v[166:167] op_sel_hi:[1,0]
	v_pk_mul_f32 v[22:23], v[22:23], v[166:167] op_sel_hi:[1,0]
	v_pk_mul_f32 v[24:25], v[24:25], v[166:167] op_sel_hi:[1,0]
	v_pk_mul_f32 v[26:27], v[26:27], v[166:167] op_sel_hi:[1,0]
	v_pk_mul_f32 v[28:29], v[28:29], v[166:167] op_sel_hi:[1,0]
	v_pk_mul_f32 v[30:31], v[30:31], v[166:167] op_sel_hi:[1,0]
; #define AT_STEP(SC0, SC1, SN0, SN1, t, DOK, DOV) do { \
;             if (DOK) AT_GLOADK(((t) + 2) * 64); \
;             if (DOV) { AT_GLOADV(((t) + 1) * 64); AT_QK(SN0, SN1, ((t) + 1) & 1); } \
;             AT_SMPV(SC0, SC1, (t) & 1); \
;             if (DOK) AT_WRITEK((t) & 1); \
;             if (DOV) AT_WRITEV(((t) + 1) & 1); \
;             __syncthreads(); } while (0)
; template <bool MLA>
; DI void attn_phase(const int TID, const int BID, LAS unsigned char* lds, const Params& p, bool need_ctx) {
;     ...
;         AT_STEP(sa0, sa1, sb0, sb1, t, false, true);
;         AT_STEP(sb0, sb1, sa0, sa1, t + 1, false, false);
.Lagqa_noresc_9:
	s_waitcnt lgkmcnt(0)
	s_barrier
	s_mov_b32 s55, s52
	s_mov_b32 s52, s53
	s_mov_b32 s53, s54
	s_mov_b32 s54, s55
	s_mov_b32 s9, 0
	v_mfma_f32_32x32x16_bf16 v[0:15], v[176:179], v[96:99], v[0:15]
	v_add_u32_e32 v222, s53, v220
	v_max3_f32 v168, v64, v65, v66
	v_max3_f32 v170, v80, v81, v82
	v_max3_f32 v168, v168, v67, v68
	v_max3_f32 v170, v170, v83, v84
	v_max3_f32 v168, v168, v69, v70
	v_max3_f32 v170, v170, v85, v86
	v_max3_f32 v168, v168, v71, v72
	v_max3_f32 v170, v170, v87, v88
	v_max3_f32 v168, v168, v73, v74
	ds_read_b64_tr_b16 v[184:185], v223 offset:6144
	ds_read_b64_tr_b16 v[186:187], v223 offset:7680
	ds_read_b64_tr_b16 v[188:189], v223 offset:6208
	ds_read_b64_tr_b16 v[190:191], v223 offset:7744
	v_mfma_f32_32x32x16_bf16 v[16:31], v[180:183], v[96:99], v[16:31]
	v_max3_f32 v170, v170, v89, v90
	v_max3_f32 v168, v168, v75, v76
	v_max3_f32 v170, v170, v91, v92
	v_max3_f32 v168, v168, v77, v78
	v_max3_f32 v170, v170, v93, v94
	v_max_f32_e32 v168, v168, v79
	v_max_f32_e32 v170, v170, v95
	v_max_f32_e32 v168, v168, v170
	v_mov_b32_e32 v170, v168
	s_nop 1
	v_permlane32_swap_b32_e32 v168, v170
	v_max_f32_e32 v168, v168, v170
	v_mul_f32_e32 v168, 0x3e38aa3b, v168
	v_cmp_gt_f32_e32 vcc, v168, v164
	s_cbranch_vccz .Lagqa_nors_10
	v_max_f32_e32 v170, v162, v168
	v_sub_f32_e32 v166, v162, v170
	v_exp_f32_e32 v166, v166
	v_mov_b32_e32 v162, v170
	v_add_f32_e32 v164, 0x41000000, v170
	v_xor_b32_e32 v163, 0x80000000, v170
	v_mul_f32_e32 v165, v165, v166
	s_mov_b32 s9, 1
.Lagqa_nors_10:
	v_fmamk_f32 v64, v64, 0x3e38aa3b, v163
	v_fmamk_f32 v80, v80, 0x3e38aa3b, v163
	v_exp_f32_e32 v64, v64
	ds_read_b64_tr_b16 v[192:193], v223 offset:3072
	ds_read_b64_tr_b16 v[194:195], v223 offset:4608
	ds_read_b64_tr_b16 v[196:197], v223 offset:3136
	ds_read_b64_tr_b16 v[198:199], v223 offset:4672
	s_waitcnt lgkmcnt(6)
	v_mfma_f32_32x32x16_bf16 v[0:15], v[184:187], v[104:107], v[0:15]
	v_exp_f32_e32 v80, v80
	v_fmamk_f32 v65, v65, 0x3e38aa3b, v163
	v_fmamk_f32 v81, v81, 0x3e38aa3b, v163
	v_exp_f32_e32 v65, v65
	v_exp_f32_e32 v81, v81
	v_fmamk_f32 v66, v66, 0x3e38aa3b, v163
	v_fmamk_f32 v82, v82, 0x3e38aa3b, v163
	v_exp_f32_e32 v66, v66
	v_exp_f32_e32 v82, v82
	v_add_f32_e32 v171, v64, v65
	v_add_f32_e32 v172, v80, v81
	v_cvt_pk_bf16_f32 v96, v64, v65
	v_fmamk_f32 v67, v67, 0x3e38aa3b, v163
	v_fmamk_f32 v83, v83, 0x3e38aa3b, v163
	v_exp_f32_e32 v67, v67
	v_exp_f32_e32 v83, v83
	ds_read_b64_tr_b16 v[200:201], v223 offset:9216
	ds_read_b64_tr_b16 v[202:203], v223 offset:10752
	ds_read_b64_tr_b16 v[204:205], v223 offset:9280
	ds_read_b64_tr_b16 v[206:207], v223 offset:10816
	s_waitcnt lgkmcnt(8)
	v_mfma_f32_32x32x16_bf16 v[16:31], v[188:191], v[104:107], v[16:31]
	v_cvt_pk_bf16_f32 v104, v80, v81
	v_fmamk_f32 v68, v68, 0x3e38aa3b, v163
	v_fmamk_f32 v84, v84, 0x3e38aa3b, v163
	v_exp_f32_e32 v68, v68
	v_exp_f32_e32 v84, v84
	v_add_f32_e32 v171, v171, v66
	v_add_f32_e32 v172, v172, v82
	v_add_f32_e32 v171, v171, v67
	v_add_f32_e32 v172, v172, v83
	v_cvt_pk_bf16_f32 v97, v66, v67
	v_cvt_pk_bf16_f32 v105, v82, v83
	v_fmamk_f32 v69, v69, 0x3e38aa3b, v163
	v_fmamk_f32 v85, v85, 0x3e38aa3b, v163
	v_exp_f32_e32 v69, v69
	v_exp_f32_e32 v85, v85
	v_fmamk_f32 v70, v70, 0x3e38aa3b, v163
	v_fmamk_f32 v86, v86, 0x3e38aa3b, v163
	v_exp_f32_e32 v70, v70
	v_exp_f32_e32 v86, v86
	s_waitcnt lgkmcnt(6)
	v_mfma_f32_32x32x16_bf16 v[0:15], v[192:195], v[100:103], v[0:15]
	v_add_f32_e32 v171, v171, v68
	v_add_f32_e32 v172, v172, v84
	v_add_f32_e32 v171, v171, v69
	v_add_f32_e32 v172, v172, v85
	v_cvt_pk_bf16_f32 v98, v68, v69
	v_cvt_pk_bf16_f32 v106, v84, v85
	v_fmamk_f32 v71, v71, 0x3e38aa3b, v163
	v_fmamk_f32 v87, v87, 0x3e38aa3b, v163
	v_exp_f32_e32 v71, v71
	v_exp_f32_e32 v87, v87
	v_fmamk_f32 v72, v72, 0x3e38aa3b, v163
	v_fmamk_f32 v88, v88, 0x3e38aa3b, v163
	v_exp_f32_e32 v72, v72
	v_exp_f32_e32 v88, v88
	v_add_f32_e32 v171, v171, v70
	v_add_f32_e32 v172, v172, v86
	v_add_f32_e32 v171, v171, v71
	v_add_f32_e32 v172, v172, v87
	v_cvt_pk_bf16_f32 v99, v70, v71
	s_waitcnt lgkmcnt(4)
	v_mfma_f32_32x32x16_bf16 v[16:31], v[196:199], v[100:103], v[16:31]
	v_cvt_pk_bf16_f32 v107, v86, v87
	v_fmamk_f32 v73, v73, 0x3e38aa3b, v163
	v_fmamk_f32 v89, v89, 0x3e38aa3b, v163
	v_exp_f32_e32 v73, v73
	v_exp_f32_e32 v89, v89
	v_fmamk_f32 v74, v74, 0x3e38aa3b, v163
	v_fmamk_f32 v90, v90, 0x3e38aa3b, v163
	v_exp_f32_e32 v74, v74
	v_exp_f32_e32 v90, v90
	v_add_f32_e32 v171, v171, v72
	v_add_f32_e32 v172, v172, v88
	v_add_f32_e32 v171, v171, v73
	v_add_f32_e32 v172, v172, v89
	v_cvt_pk_bf16_f32 v100, v72, v73
	v_fmamk_f32 v75, v75, 0x3e38aa3b, v163
	v_fmamk_f32 v91, v91, 0x3e38aa3b, v163
	v_exp_f32_e32 v75, v75
	v_exp_f32_e32 v91, v91
	ds_read_b64_tr_b16 v[176:177], v222 offset:0
	ds_read_b64_tr_b16 v[178:179], v222 offset:1536
	ds_read_b64_tr_b16 v[180:181], v222 offset:64
	ds_read_b64_tr_b16 v[182:183], v222 offset:1600
	s_waitcnt lgkmcnt(6)
	v_mfma_f32_32x32x16_bf16 v[0:15], v[200:203], v[108:111], v[0:15]
	v_fmamk_f32 v76, v76, 0x3e38aa3b, v163
	v_fmamk_f32 v92, v92, 0x3e38aa3b, v163
	v_exp_f32_e32 v76, v76
	v_exp_f32_e32 v92, v92
	v_add_f32_e32 v171, v171, v74
	v_add_f32_e32 v172, v172, v90
	v_add_f32_e32 v171, v171, v75
	v_add_f32_e32 v172, v172, v91
	v_cvt_pk_bf16_f32 v101, v74, v75
	v_fmamk_f32 v77, v77, 0x3e38aa3b, v163
	v_fmamk_f32 v93, v93, 0x3e38aa3b, v163
	v_exp_f32_e32 v77, v77
	v_exp_f32_e32 v93, v93
	v_fmamk_f32 v78, v78, 0x3e38aa3b, v163
	v_fmamk_f32 v94, v94, 0x3e38aa3b, v163
	v_exp_f32_e32 v78, v78
	v_exp_f32_e32 v94, v94
	s_waitcnt lgkmcnt(4)
	v_mfma_f32_32x32x16_bf16 v[16:31], v[204:207], v[108:111], v[16:31]
	v_cvt_pk_bf16_f32 v108, v88, v89
	v_cvt_pk_bf16_f32 v109, v90, v91
	v_add_f32_e32 v171, v171, v76
	v_add_f32_e32 v172, v172, v92
	v_add_f32_e32 v171, v171, v77
	v_add_f32_e32 v172, v172, v93
	v_cvt_pk_bf16_f32 v102, v76, v77
	v_cvt_pk_bf16_f32 v110, v92, v93
	v_fmamk_f32 v79, v79, 0x3e38aa3b, v163
	v_fmamk_f32 v95, v95, 0x3e38aa3b, v163
	v_exp_f32_e32 v79, v79
	v_exp_f32_e32 v95, v95
	v_add_f32_e32 v171, v171, v78
	v_add_f32_e32 v172, v172, v94
	v_add_f32_e32 v171, v171, v79
	v_add_f32_e32 v172, v172, v95
	v_cvt_pk_bf16_f32 v103, v78, v79
	v_cvt_pk_bf16_f32 v111, v94, v95
	v_add_f32_e32 v165, v165, v171
	v_add_f32_e32 v165, v165, v172
	s_cmp_lg_u32 s9, 0
	s_cbranch_scc0 .Lagqa_noresc_11
; #define AT_STEP(SC0, SC1, SN0, SN1, t, DOK, DOV) do { \
;             if (DOK) AT_GLOADK(((t) + 2) * 64); \
;             if (DOV) { AT_GLOADV(((t) + 1) * 64); AT_QK(SN0, SN1, ((t) + 1) & 1); } \
;             AT_SMPV(SC0, SC1, (t) & 1); \
;             if (DOK) AT_WRITEK((t) & 1); \
;             if (DOV) AT_WRITEV(((t) + 1) & 1); \
;             __syncthreads(); } while (0)
; #define AT_PK4(OX, jg) u32x2 { pk_bf16(OX[4 * (jg)] * inv, OX[4 * (jg) + 1] * inv), pk_bf16(OX[4 * (jg) + 2] * inv, OX[4 * (jg) + 3] * inv) }
; template <bool MLA>
; DI void attn_phase(const int TID, const int BID, LAS unsigned char* lds, const Params& p, bool need_ctx) {
;     ...
;         AT_STEP(sb0, sb1, sa0, sa1, t + 1, false, false);
;         __builtin_amdgcn_s_setprio(0);
;         lsum = xsum32(lsum);
;         const float inv = 1.f / lsum;
;         bf16_t* op = O + (size_t)(row0 + wid * 32 + r) * 1024 + head * 64 + 8 * hh;
;     ...
; #pragma unroll
;         for (int k = 0; k < 2; ++k) {
;             const u32x2 a = AT_PK4(o0, 2 * k), b2 = AT_PK4(o0, 2 * k + 1), c = AT_PK4(o1, 2 * k), d = AT_PK4(o1, 2 * k + 1);
;             const u32x2 s0 = __builtin_amdgcn_permlane32_swap(a[0], b2[0], false, false), s1 = __builtin_amdgcn_permlane32_swap(a[1], b2[1], false, false);
;             const u32x2 t0 = __builtin_amdgcn_permlane32_swap(c[0], d[0], false, false), t1 = __builtin_amdgcn_permlane32_swap(c[1], d[1], false, false);
;             const u32x4 w0 = {s0[0], s1[0], s0[1], s1[1]}, w1 = {t0[0], t1[0], t0[1], t1[1]};
;             *(u32x4*)(op + 16 * k) = w0; *(u32x4*)(op + 32 + 16 * k) = w1;
;         }
	s_nop 15
	v_pk_mul_f32 v[0:1], v[0:1], v[166:167] op_sel_hi:[1,0]
	v_pk_mul_f32 v[2:3], v[2:3], v[166:167] op_sel_hi:[1,0]
	v_pk_mul_f32 v[4:5], v[4:5], v[166:167] op_sel_hi:[1,0]
	v_pk_mul_f32 v[6:7], v[6:7], v[166:167] op_sel_hi:[1,0]
	v_pk_mul_f32 v[8:9], v[8:9], v[166:167] op_sel_hi:[1,0]
	v_pk_mul_f32 v[10:11], v[10:11], v[166:167] op_sel_hi:[1,0]
	v_pk_mul_f32 v[12:13], v[12:13], v[166:167] op_sel_hi:[1,0]
	v_pk_mul_f32 v[14:15], v[14:15], v[166:167] op_sel_hi:[1,0]
	v_pk_mul_f32 v[16:17], v[16:17], v[166:167] op_sel_hi:[1,0]
	v_pk_mul_f32 v[18:19], v[18:19], v[166:167] op_sel_hi:[1,0]
	v_pk_mul_f32 v[20:21], v[20:21], v[166:167] op_sel_hi:[1,0]
	v_pk_mul_f32 v[22:23], v[22:23], v[166:167] op_sel_hi:[1,0]
	v_pk_mul_f32 v[24:25], v[24:25], v[166:167] op_sel_hi:[1,0]
	v_pk_mul_f32 v[26:27], v[26:27], v[166:167] op_sel_hi:[1,0]
	v_pk_mul_f32 v[28:29], v[28:29], v[166:167] op_sel_hi:[1,0]
	v_pk_mul_f32 v[30:31], v[30:31], v[166:167] op_sel_hi:[1,0]
.Lagqa_noresc_11:
	s_waitcnt lgkmcnt(0)
	s_barrier
	s_mov_b32 s55, s52
	s_mov_b32 s52, s53
	s_mov_b32 s53, s54
	s_mov_b32 s54, s55
	v_mfma_f32_32x32x16_bf16 v[0:15], v[176:179], v[96:99], v[0:15]
	ds_read_b64_tr_b16 v[184:185], v222 offset:6144
	ds_read_b64_tr_b16 v[186:187], v222 offset:7680
	ds_read_b64_tr_b16 v[188:189], v222 offset:6208
	ds_read_b64_tr_b16 v[190:191], v222 offset:7744
	v_mfma_f32_32x32x16_bf16 v[16:31], v[180:183], v[96:99], v[16:31]
	ds_read_b64_tr_b16 v[192:193], v222 offset:3072
	ds_read_b64_tr_b16 v[194:195], v222 offset:4608
	ds_read_b64_tr_b16 v[196:197], v222 offset:3136
	ds_read_b64_tr_b16 v[198:199], v222 offset:4672
	s_waitcnt lgkmcnt(6)
	v_mfma_f32_32x32x16_bf16 v[0:15], v[184:187], v[104:107], v[0:15]
	ds_read_b64_tr_b16 v[200:201], v222 offset:9216
	ds_read_b64_tr_b16 v[202:203], v222 offset:10752
	ds_read_b64_tr_b16 v[204:205], v222 offset:9280
	ds_read_b64_tr_b16 v[206:207], v222 offset:10816
	s_waitcnt lgkmcnt(8)
	v_mfma_f32_32x32x16_bf16 v[16:31], v[188:191], v[104:107], v[16:31]
	s_waitcnt lgkmcnt(6)
	v_mfma_f32_32x32x16_bf16 v[0:15], v[192:195], v[100:103], v[0:15]
	s_waitcnt lgkmcnt(4)
	v_mfma_f32_32x32x16_bf16 v[16:31], v[196:199], v[100:103], v[16:31]
	s_waitcnt lgkmcnt(2)
	v_mfma_f32_32x32x16_bf16 v[0:15], v[200:203], v[108:111], v[0:15]
	s_waitcnt lgkmcnt(0)
	v_mfma_f32_32x32x16_bf16 v[16:31], v[204:207], v[108:111], v[16:31]
	s_setprio 0
	v_mov_b32_e32 v173, v165
	s_nop 1
	v_permlane32_swap_b32_e32 v165, v173
	v_add_f32_e32 v165, v165, v173
	v_div_scale_f32 v230, s[60:61], v165, v165, 1.0
	v_rcp_f32_e32 v231, v230
	s_nop 0
	v_fma_f32 v232, -v230, v231, 1.0
	v_fmac_f32_e32 v231, v232, v231
	v_div_scale_f32 v232, vcc, 1.0, v165, 1.0
	v_mul_f32_e32 v233, v232, v231
	v_fma_f32 v173, -v230, v233, v232
	v_fmac_f32_e32 v233, v173, v231
	v_fma_f32 v230, -v230, v233, v232
	s_nop 1
	v_div_fmas_f32 v230, v230, v231, v233
	v_div_fixup_f32 v166, v230, v165, 1.0
	v_pk_mul_f32 v[0:1], v[0:1], v[166:167] op_sel_hi:[1,0]
	v_pk_mul_f32 v[2:3], v[2:3], v[166:167] op_sel_hi:[1,0]
	v_pk_mul_f32 v[4:5], v[4:5], v[166:167] op_sel_hi:[1,0]
	v_pk_mul_f32 v[6:7], v[6:7], v[166:167] op_sel_hi:[1,0]
	v_pk_mul_f32 v[8:9], v[8:9], v[166:167] op_sel_hi:[1,0]
	v_pk_mul_f32 v[10:11], v[10:11], v[166:167] op_sel_hi:[1,0]
	v_pk_mul_f32 v[12:13], v[12:13], v[166:167] op_sel_hi:[1,0]
	v_pk_mul_f32 v[14:15], v[14:15], v[166:167] op_sel_hi:[1,0]
	v_pk_mul_f32 v[16:17], v[16:17], v[166:167] op_sel_hi:[1,0]
	v_pk_mul_f32 v[18:19], v[18:19], v[166:167] op_sel_hi:[1,0]
	v_pk_mul_f32 v[20:21], v[20:21], v[166:167] op_sel_hi:[1,0]
	v_pk_mul_f32 v[22:23], v[22:23], v[166:167] op_sel_hi:[1,0]
	v_pk_mul_f32 v[24:25], v[24:25], v[166:167] op_sel_hi:[1,0]
	v_pk_mul_f32 v[26:27], v[26:27], v[166:167] op_sel_hi:[1,0]
	v_pk_mul_f32 v[28:29], v[28:29], v[166:167] op_sel_hi:[1,0]
	v_pk_mul_f32 v[30:31], v[30:31], v[166:167] op_sel_hi:[1,0]
	v_cvt_pk_bf16_f32 v96, v0, v1
	v_cvt_pk_bf16_f32 v97, v2, v3
	v_cvt_pk_bf16_f32 v98, v4, v5
	v_cvt_pk_bf16_f32 v99, v6, v7
	v_cvt_pk_bf16_f32 v100, v16, v17
	v_cvt_pk_bf16_f32 v101, v18, v19
	v_cvt_pk_bf16_f32 v102, v20, v21
	v_cvt_pk_bf16_f32 v103, v22, v23
	v_cvt_pk_bf16_f32 v104, v8, v9
	v_cvt_pk_bf16_f32 v105, v10, v11
	v_cvt_pk_bf16_f32 v106, v12, v13
	v_cvt_pk_bf16_f32 v107, v14, v15
	v_cvt_pk_bf16_f32 v108, v24, v25
	v_cvt_pk_bf16_f32 v109, v26, v27
	v_cvt_pk_bf16_f32 v110, v28, v29
	v_cvt_pk_bf16_f32 v111, v30, v31
	s_nop 1
	v_permlane32_swap_b32_e32 v96, v98
	v_permlane32_swap_b32_e32 v97, v99
	v_permlane32_swap_b32_e32 v100, v102
	v_permlane32_swap_b32_e32 v101, v103
	v_permlane32_swap_b32_e32 v104, v106
	v_permlane32_swap_b32_e32 v105, v107
	v_permlane32_swap_b32_e32 v108, v110
	v_permlane32_swap_b32_e32 v109, v111
	global_store_dwordx4 v228, v[96:99], s[16:17]
	global_store_dwordx4 v228, v[100:103], s[16:17] offset:64
	global_store_dwordx4 v228, v[104:107], s[16:17] offset:32
	global_store_dwordx4 v228, v[108:111], s[16:17] offset:96
	s_add_i32 s6, s6, s31
	s_cmp_ge_i32 s6, s8
	s_cbranch_scc0 .Lagqa_item
.Lagqa_done:
	s_branch .LBB0_339
